# GEMM K-loops: second lgkmcnt(0) after the barrier removed (no LDS op between it and the wait before the barrier)
# baseline (speedup 1.0000x reference)
; #define PG8_STAGE(bufoff, gbase, voff) do { _Pragma("unroll") for (int _i = 0; _i < 2; ++_i) \
;         __builtin_amdgcn_global_load_lds((const unsigned*)((const char*)(gbase) + (voff)[_i]), (PG8_LAS unsigned*)(lds + (bufoff) + ldsw + _i * 8192), 16, 0, 0); } while (0)
; #define PG8_LDA(dst, b, h) do { _Pragma("unroll") for (int m = 0; m < 4; ++m) _Pragma("unroll") for (int k = 0; k < 2; ++k) dst[m][k] = *(const PG8_LAS bf16x8*)(lds + PG8_SA(b, h) + aoff + m * 2048 + k * 1024); } while (0)
; #define PG8_LDB(dst, b, h) do { _Pragma("unroll") for (int n = 0; n < 2; ++n) _Pragma("unroll") for (int k = 0; k < 2; ++k) dst[n][k] = *(const PG8_LAS bf16x8*)(lds + PG8_SB(b, h) + boff + n * 2048 + k * 1024); } while (0)
; #define PG8_MMA(ai, bj, At, Bt) do { __builtin_amdgcn_s_setprio(1); _Pragma("unroll") for (int m = 0; m < 4; ++m) _Pragma("unroll") for (int n = 0; n < 2; ++n) _Pragma("unroll") for (int k = 0; k < 2; ++k) \
;         acc[ai][bj][m][n] = __builtin_amdgcn_mfma_f32_16x16x32_bf16(Bt[n][k], At[m][k], acc[ai][bj][m][n], 0, 0, 0); __builtin_amdgcn_s_setprio(0); } while (0)
; #define PG8_WAIT_V(n) asm volatile("s_waitcnt vmcnt(" #n ")" ::: "memory")
; #define PG8_WAIT_L(n) asm volatile("s_waitcnt lgkmcnt(" #n ")" ::: "memory")
; #define PG8_BAR __builtin_amdgcn_s_barrier()
; #define PG8_SCHED __builtin_amdgcn_sched_barrier(0)
; template <class Epi, class Sched, bool ALIGN_EPI = false, bool SP2 = false>
; __device__ __forceinline__ void gemm_phase(PG8_LAS unsigned char* lds, const Gemm g, const Sched& S, const Epi& E) {
;     ...
;             if constexpr (SP2) {
;             PG8_LDB(B0, 0, 0); PG8_LDB(B1, 0, 1); PG8_SCHED; PG8_LDA(At, 0, 0); PG8_STAGE(PG8_SA(1, 1), a1 + hstep, voffA);
;             PG8_WAIT_V(8); PG8_WAIT_L(0); PG8_BAR; PG8_MMA(0, 0, At, B0); PG8_MMA(0, 1, At, B1); PG8_BAR; PG8_SCHED;
;             PG8_LDA(At, 0, 1); PG8_STAGE(PG8_SB(0, 0), b2, voffB); PG8_STAGE(PG8_SB(0, 1), b2 + hstepB, voffB); PG8_STAGE(PG8_SA(0, 0), a2, voffA);
;             PG8_WAIT_V(8); PG8_WAIT_L(0); PG8_BAR; PG8_MMA(1, 0, At, B0); PG8_MMA(1, 1, At, B1); PG8_BAR; PG8_SCHED;
.LBB0_219:
	ds_read_b128 v[128:131], v196
	ds_read_b128 v[132:135], v196 offset:1024
	ds_read_b128 v[136:139], v196 offset:2048
	ds_read_b128 v[140:143], v196 offset:3072
	ds_read_b128 v[144:147], v197
	ds_read_b128 v[148:151], v197 offset:1024
	ds_read_b128 v[152:155], v197 offset:2048
	ds_read_b128 v[156:159], v197 offset:3072
	s_add_u32 s44, s10, 0xfffc0080
	s_addc_u32 s45, s11, -1
	s_cmp_eq_u32 s69, 12
	s_cselect_b32 s47, s1, s45
	s_cselect_b32 s46, s4, s44
	s_cselect_b32 s45, s33, s68
	s_cselect_b32 s44, s37, s39
	v_lshl_add_u64 v[230:231], s[10:11], 0, v[174:175]
	s_add_i32 m0, s55, 0xc000
	ds_read_b128 v[160:163], v198
	ds_read_b128 v[202:205], v198 offset:1024
	ds_read_b128 v[206:209], v198 offset:2048
	ds_read_b128 v[210:213], v198 offset:3072
	ds_read_b128 v[214:217], v198 offset:4096
	ds_read_b128 v[218:221], v198 offset:5120
	ds_read_b128 v[222:225], v198 offset:6144
	ds_read_b128 v[226:229], v198 offset:7168
	global_load_lds_dwordx4 v[230:231], off
	v_lshl_add_u64 v[230:231], s[10:11], 0, v[178:179]
	s_add_i32 m0, s55, 0xe000
	s_nop 0
	global_load_lds_dwordx4 v[230:231], off
	s_waitcnt vmcnt(8)
	s_waitcnt lgkmcnt(0)
	s_barrier
	s_setprio 1
	v_mfma_f32_16x16x32_bf16 v[124:127], v[128:131], v[160:163], v[124:127]
	v_mfma_f32_16x16x32_bf16 v[120:123], v[136:139], v[160:163], v[120:123]
	v_mfma_f32_16x16x32_bf16 v[108:111], v[128:131], v[206:209], v[108:111]
	v_mfma_f32_16x16x32_bf16 v[104:107], v[136:139], v[206:209], v[104:107]
	v_mfma_f32_16x16x32_bf16 v[92:95], v[128:131], v[214:217], v[92:95]
	v_mfma_f32_16x16x32_bf16 v[88:91], v[136:139], v[214:217], v[88:91]
	v_mfma_f32_16x16x32_bf16 v[76:79], v[128:131], v[222:225], v[76:79]
	v_mfma_f32_16x16x32_bf16 v[72:75], v[136:139], v[222:225], v[72:75]
	v_mfma_f32_16x16x32_bf16 v[124:127], v[132:135], v[202:205], v[124:127]
	v_mfma_f32_16x16x32_bf16 v[120:123], v[140:143], v[202:205], v[120:123]
	v_mfma_f32_16x16x32_bf16 v[108:111], v[132:135], v[210:213], v[108:111]
	v_mfma_f32_16x16x32_bf16 v[104:107], v[140:143], v[210:213], v[104:107]
	v_mfma_f32_16x16x32_bf16 v[92:95], v[132:135], v[218:221], v[92:95]
	v_mfma_f32_16x16x32_bf16 v[88:91], v[140:143], v[218:221], v[88:91]
	v_mfma_f32_16x16x32_bf16 v[76:79], v[132:135], v[226:229], v[76:79]
	v_mfma_f32_16x16x32_bf16 v[72:75], v[140:143], v[226:229], v[72:75]
	s_setprio 0
	s_setprio 1
	v_mfma_f32_16x16x32_bf16 v[116:119], v[144:147], v[160:163], v[116:119]
	v_mfma_f32_16x16x32_bf16 v[112:115], v[152:155], v[160:163], v[112:115]
	v_mfma_f32_16x16x32_bf16 v[100:103], v[144:147], v[206:209], v[100:103]
	v_mfma_f32_16x16x32_bf16 v[96:99], v[152:155], v[206:209], v[96:99]
	v_mfma_f32_16x16x32_bf16 v[84:87], v[144:147], v[214:217], v[84:87]
	v_mfma_f32_16x16x32_bf16 v[80:83], v[152:155], v[214:217], v[80:83]
	v_mfma_f32_16x16x32_bf16 v[68:71], v[144:147], v[222:225], v[68:71]
	v_mfma_f32_16x16x32_bf16 v[64:67], v[152:155], v[222:225], v[64:67]
	v_mfma_f32_16x16x32_bf16 v[116:119], v[148:151], v[202:205], v[116:119]
	v_mfma_f32_16x16x32_bf16 v[112:115], v[156:159], v[202:205], v[112:115]
	v_mfma_f32_16x16x32_bf16 v[100:103], v[148:151], v[210:213], v[100:103]
	v_mfma_f32_16x16x32_bf16 v[96:99], v[156:159], v[210:213], v[96:99]
	v_mfma_f32_16x16x32_bf16 v[84:87], v[148:151], v[218:221], v[84:87]
	v_mfma_f32_16x16x32_bf16 v[80:83], v[156:159], v[218:221], v[80:83]
	v_mfma_f32_16x16x32_bf16 v[68:71], v[148:151], v[226:229], v[68:71]
	v_mfma_f32_16x16x32_bf16 v[64:67], v[156:159], v[226:229], v[64:67]
	s_setprio 0
	s_barrier
	s_add_i32 s70, s67, s53
	v_lshl_add_u64 v[230:231], s[44:45], 0, v[166:167]
	s_mov_b32 m0, s70
	ds_read_b128 v[160:163], v198 offset:16384
	ds_read_b128 v[202:205], v198 offset:17408
	ds_read_b128 v[206:209], v198 offset:18432
	ds_read_b128 v[210:213], v198 offset:19456
	ds_read_b128 v[214:217], v198 offset:20480
	ds_read_b128 v[218:221], v198 offset:21504
	ds_read_b128 v[222:225], v198 offset:22528
	ds_read_b128 v[226:229], v198 offset:23552
	global_load_lds_dwordx4 v[230:231], off
	s_add_i32 m0, s70, 0x2000
	s_add_u32 s70, s44, 0x10000
	v_lshl_add_u64 v[232:233], s[44:45], 0, v[170:171]
	s_addc_u32 s71, s45, 0
	s_add_i32 s76, s72, s53
	global_load_lds_dwordx4 v[232:233], off
	v_lshl_add_u64 v[234:235], s[70:71], 0, v[166:167]
	s_mov_b32 m0, s76
	v_lshl_add_u64 v[236:237], s[46:47], 0, v[168:169]
	global_load_lds_dwordx4 v[234:235], off
	v_lshl_add_u64 v[234:235], s[70:71], 0, v[170:171]
	s_add_i32 m0, s76, 0x2000
	s_nop 0
	global_load_lds_dwordx4 v[234:235], off
	v_lshl_add_u64 v[234:235], s[46:47], 0, v[164:165]
	s_mov_b32 m0, s55
	s_nop 0
	global_load_lds_dwordx4 v[234:235], off
	s_mov_b32 m0, s56
	s_nop 0
	global_load_lds_dwordx4 v[236:237], off
	s_waitcnt vmcnt(8)
	s_waitcnt lgkmcnt(0)
	s_barrier
; #define PG8_STAGE(bufoff, gbase, voff) do { _Pragma("unroll") for (int _i = 0; _i < 2; ++_i) \
;         __builtin_amdgcn_global_load_lds((const unsigned*)((const char*)(gbase) + (voff)[_i]), (PG8_LAS unsigned*)(lds + (bufoff) + ldsw + _i * 8192), 16, 0, 0); } while (0)
; #define PG8_LDA(dst, b, h) do { _Pragma("unroll") for (int m = 0; m < 4; ++m) _Pragma("unroll") for (int k = 0; k < 2; ++k) dst[m][k] = *(const PG8_LAS bf16x8*)(lds + PG8_SA(b, h) + aoff + m * 2048 + k * 1024); } while (0)
; #define PG8_LDB(dst, b, h) do { _Pragma("unroll") for (int n = 0; n < 2; ++n) _Pragma("unroll") for (int k = 0; k < 2; ++k) dst[n][k] = *(const PG8_LAS bf16x8*)(lds + PG8_SB(b, h) + boff + n * 2048 + k * 1024); } while (0)
; #define PG8_MMA(ai, bj, At, Bt) do { __builtin_amdgcn_s_setprio(1); _Pragma("unroll") for (int m = 0; m < 4; ++m) _Pragma("unroll") for (int n = 0; n < 2; ++n) _Pragma("unroll") for (int k = 0; k < 2; ++k) \
;         acc[ai][bj][m][n] = __builtin_amdgcn_mfma_f32_16x16x32_bf16(Bt[n][k], At[m][k], acc[ai][bj][m][n], 0, 0, 0); __builtin_amdgcn_s_setprio(0); } while (0)
; #define PG8_WAIT_V(n) asm volatile("s_waitcnt vmcnt(" #n ")" ::: "memory")
; #define PG8_WAIT_L(n) asm volatile("s_waitcnt lgkmcnt(" #n ")" ::: "memory")
; #define PG8_BAR __builtin_amdgcn_s_barrier()
; #define PG8_SCHED __builtin_amdgcn_sched_barrier(0)
; template <class Epi, class Sched, bool ALIGN_EPI = false, bool SP2 = false>
; __device__ __forceinline__ void gemm_phase(PG8_LAS unsigned char* lds, const Gemm g, const Sched& S, const Epi& E) {
;     ...
;             PG8_WAIT_V(8); PG8_WAIT_L(0); PG8_BAR; PG8_MMA(1, 0, At, B0); PG8_MMA(1, 1, At, B1); PG8_BAR; PG8_SCHED;
;             PG8_LDB(B0, 1, 0); PG8_LDB(B1, 1, 1); PG8_SCHED; PG8_LDA(At, 1, 0); PG8_STAGE(PG8_SA(0, 1), a2 + hstep, voffA);
;             PG8_WAIT_V(8); PG8_WAIT_L(0); PG8_BAR; PG8_MMA(0, 0, At, B0); PG8_MMA(0, 1, At, B1); PG8_BAR; PG8_SCHED;
	s_setprio 1
	v_mfma_f32_16x16x32_bf16 v[60:63], v[128:131], v[160:163], v[60:63]
	v_mfma_f32_16x16x32_bf16 v[56:59], v[136:139], v[160:163], v[56:59]
	v_mfma_f32_16x16x32_bf16 v[44:47], v[128:131], v[206:209], v[44:47]
	v_mfma_f32_16x16x32_bf16 v[40:43], v[136:139], v[206:209], v[40:43]
	v_mfma_f32_16x16x32_bf16 v[28:31], v[128:131], v[214:217], v[28:31]
	v_mfma_f32_16x16x32_bf16 v[24:27], v[136:139], v[214:217], v[24:27]
	v_mfma_f32_16x16x32_bf16 v[12:15], v[128:131], v[222:225], v[12:15]
	v_mfma_f32_16x16x32_bf16 v[8:11], v[136:139], v[222:225], v[8:11]
	v_mfma_f32_16x16x32_bf16 v[60:63], v[132:135], v[202:205], v[60:63]
	v_mfma_f32_16x16x32_bf16 v[56:59], v[140:143], v[202:205], v[56:59]
	v_mfma_f32_16x16x32_bf16 v[44:47], v[132:135], v[210:213], v[44:47]
	v_mfma_f32_16x16x32_bf16 v[40:43], v[140:143], v[210:213], v[40:43]
	v_mfma_f32_16x16x32_bf16 v[28:31], v[132:135], v[218:221], v[28:31]
	v_mfma_f32_16x16x32_bf16 v[24:27], v[140:143], v[218:221], v[24:27]
	v_mfma_f32_16x16x32_bf16 v[12:15], v[132:135], v[226:229], v[12:15]
	v_mfma_f32_16x16x32_bf16 v[8:11], v[140:143], v[226:229], v[8:11]
	s_setprio 0
	s_setprio 1
	v_mfma_f32_16x16x32_bf16 v[52:55], v[144:147], v[160:163], v[52:55]
	v_mfma_f32_16x16x32_bf16 v[48:51], v[152:155], v[160:163], v[48:51]
	v_mfma_f32_16x16x32_bf16 v[36:39], v[144:147], v[206:209], v[36:39]
	v_mfma_f32_16x16x32_bf16 v[32:35], v[152:155], v[206:209], v[32:35]
	v_mfma_f32_16x16x32_bf16 v[20:23], v[144:147], v[214:217], v[20:23]
	v_mfma_f32_16x16x32_bf16 v[16:19], v[152:155], v[214:217], v[16:19]
	v_mfma_f32_16x16x32_bf16 v[4:7], v[144:147], v[222:225], v[4:7]
	v_mfma_f32_16x16x32_bf16 v[0:3], v[152:155], v[222:225], v[0:3]
	v_mfma_f32_16x16x32_bf16 v[52:55], v[148:151], v[202:205], v[52:55]
	v_mfma_f32_16x16x32_bf16 v[48:51], v[156:159], v[202:205], v[48:51]
	v_mfma_f32_16x16x32_bf16 v[36:39], v[148:151], v[210:213], v[36:39]
	v_mfma_f32_16x16x32_bf16 v[32:35], v[156:159], v[210:213], v[32:35]
	v_mfma_f32_16x16x32_bf16 v[20:23], v[148:151], v[218:221], v[20:23]
	v_mfma_f32_16x16x32_bf16 v[16:19], v[156:159], v[218:221], v[16:19]
	v_mfma_f32_16x16x32_bf16 v[4:7], v[148:151], v[226:229], v[4:7]
	v_mfma_f32_16x16x32_bf16 v[0:3], v[156:159], v[226:229], v[0:3]
	s_setprio 0
	s_barrier
	s_add_i32 s70, 0, 0x18000
	s_add_i32 s71, 0, 0x1c000
	v_add_u32_e32 v140, s70, v193
	v_add_u32_e32 v156, s71, v193
	ds_read_b128 v[128:131], v140
	ds_read_b128 v[132:135], v140 offset:1024
	ds_read_b128 v[136:139], v140 offset:2048
	ds_read_b128 v[140:143], v140 offset:3072
	ds_read_b128 v[144:147], v156
	ds_read_b128 v[148:151], v156 offset:1024
	ds_read_b128 v[152:155], v156 offset:2048
	ds_read_b128 v[156:159], v156 offset:3072
	s_add_u32 s46, s46, 0x40000
	s_addc_u32 s47, s47, 0
	s_mov_b32 m0, s57
	v_lshl_add_u64 v[238:239], s[46:47], 0, v[164:165]
	ds_read_b128 v[160:163], v198 offset:32768
	ds_read_b128 v[202:205], v198 offset:33792
	ds_read_b128 v[206:209], v198 offset:34816
	ds_read_b128 v[210:213], v198 offset:35840
	ds_read_b128 v[214:217], v198 offset:36864
	ds_read_b128 v[218:221], v198 offset:37888
	ds_read_b128 v[222:225], v198 offset:38912
	ds_read_b128 v[226:229], v198 offset:39936
	global_load_lds_dwordx4 v[238:239], off
	v_lshl_add_u64 v[238:239], s[46:47], 0, v[168:169]
	s_mov_b32 m0, s58
	s_nop 0
	global_load_lds_dwordx4 v[238:239], off
	s_waitcnt vmcnt(8)
	s_waitcnt lgkmcnt(0)
	s_barrier
	s_setprio 1
	v_mfma_f32_16x16x32_bf16 v[124:127], v[128:131], v[160:163], v[124:127]
	v_mfma_f32_16x16x32_bf16 v[120:123], v[136:139], v[160:163], v[120:123]
	v_mfma_f32_16x16x32_bf16 v[108:111], v[128:131], v[206:209], v[108:111]
	v_mfma_f32_16x16x32_bf16 v[104:107], v[136:139], v[206:209], v[104:107]
	v_mfma_f32_16x16x32_bf16 v[92:95], v[128:131], v[214:217], v[92:95]
	v_mfma_f32_16x16x32_bf16 v[88:91], v[136:139], v[214:217], v[88:91]
	v_mfma_f32_16x16x32_bf16 v[76:79], v[128:131], v[222:225], v[76:79]
	v_mfma_f32_16x16x32_bf16 v[72:75], v[136:139], v[222:225], v[72:75]
	v_mfma_f32_16x16x32_bf16 v[124:127], v[132:135], v[202:205], v[124:127]
	v_mfma_f32_16x16x32_bf16 v[120:123], v[140:143], v[202:205], v[120:123]
	v_mfma_f32_16x16x32_bf16 v[108:111], v[132:135], v[210:213], v[108:111]
	v_mfma_f32_16x16x32_bf16 v[104:107], v[140:143], v[210:213], v[104:107]
	v_mfma_f32_16x16x32_bf16 v[92:95], v[132:135], v[218:221], v[92:95]
	v_mfma_f32_16x16x32_bf16 v[88:91], v[140:143], v[218:221], v[88:91]
	v_mfma_f32_16x16x32_bf16 v[76:79], v[132:135], v[226:229], v[76:79]
	v_mfma_f32_16x16x32_bf16 v[72:75], v[140:143], v[226:229], v[72:75]
	s_setprio 0
	s_setprio 1
	v_mfma_f32_16x16x32_bf16 v[116:119], v[144:147], v[160:163], v[116:119]
	v_mfma_f32_16x16x32_bf16 v[112:115], v[152:155], v[160:163], v[112:115]
	v_mfma_f32_16x16x32_bf16 v[100:103], v[144:147], v[206:209], v[100:103]
	v_mfma_f32_16x16x32_bf16 v[96:99], v[152:155], v[206:209], v[96:99]
	v_mfma_f32_16x16x32_bf16 v[84:87], v[144:147], v[214:217], v[84:87]
	v_mfma_f32_16x16x32_bf16 v[80:83], v[152:155], v[214:217], v[80:83]
	v_mfma_f32_16x16x32_bf16 v[68:71], v[144:147], v[222:225], v[68:71]
	v_mfma_f32_16x16x32_bf16 v[64:67], v[152:155], v[222:225], v[64:67]
	v_mfma_f32_16x16x32_bf16 v[116:119], v[148:151], v[202:205], v[116:119]
	v_mfma_f32_16x16x32_bf16 v[112:115], v[156:159], v[202:205], v[112:115]
	v_mfma_f32_16x16x32_bf16 v[100:103], v[148:151], v[210:213], v[100:103]
	v_mfma_f32_16x16x32_bf16 v[96:99], v[156:159], v[210:213], v[96:99]
	v_mfma_f32_16x16x32_bf16 v[84:87], v[148:151], v[218:221], v[84:87]
	v_mfma_f32_16x16x32_bf16 v[80:83], v[156:159], v[218:221], v[80:83]
	v_mfma_f32_16x16x32_bf16 v[68:71], v[148:151], v[226:229], v[68:71]
	v_mfma_f32_16x16x32_bf16 v[64:67], v[156:159], v[226:229], v[64:67]
	s_setprio 0
	s_barrier
; #define PG8_STAGE(bufoff, gbase, voff) do { _Pragma("unroll") for (int _i = 0; _i < 2; ++_i) \
;         __builtin_amdgcn_global_load_lds((const unsigned*)((const char*)(gbase) + (voff)[_i]), (PG8_LAS unsigned*)(lds + (bufoff) + ldsw + _i * 8192), 16, 0, 0); } while (0)
; #define PG8_LDA(dst, b, h) do { _Pragma("unroll") for (int m = 0; m < 4; ++m) _Pragma("unroll") for (int k = 0; k < 2; ++k) dst[m][k] = *(const PG8_LAS bf16x8*)(lds + PG8_SA(b, h) + aoff + m * 2048 + k * 1024); } while (0)
; #define PG8_MMA(ai, bj, At, Bt) do { __builtin_amdgcn_s_setprio(1); _Pragma("unroll") for (int m = 0; m < 4; ++m) _Pragma("unroll") for (int n = 0; n < 2; ++n) _Pragma("unroll") for (int k = 0; k < 2; ++k) \
;         acc[ai][bj][m][n] = __builtin_amdgcn_mfma_f32_16x16x32_bf16(Bt[n][k], At[m][k], acc[ai][bj][m][n], 0, 0, 0); __builtin_amdgcn_s_setprio(0); } while (0)
; #define PG8_WAIT_V(n) asm volatile("s_waitcnt vmcnt(" #n ")" ::: "memory")
; #define PG8_WAIT_L(n) asm volatile("s_waitcnt lgkmcnt(" #n ")" ::: "memory")
; #define PG8_BAR __builtin_amdgcn_s_barrier()
; #define PG8_SCHED __builtin_amdgcn_sched_barrier(0)
; template <class Epi, class Sched, bool ALIGN_EPI = false, bool SP2 = false>
; __device__ __forceinline__ void gemm_phase(PG8_LAS unsigned char* lds, const Gemm g, const Sched& S, const Epi& E) {
;     ...
;             PG8_LDA(At, 1, 1); PG8_STAGE(PG8_SB(1, 0), b3, voffB); PG8_STAGE(PG8_SB(1, 1), b3 + hstepB, voffB); PG8_STAGE(PG8_SA(1, 0), a3, voffA);
;             PG8_WAIT_V(8); PG8_WAIT_L(0); PG8_BAR; PG8_MMA(1, 0, At, B0); PG8_MMA(1, 1, At, B1); PG8_BAR; PG8_SCHED;
;     ...
;         if constexpr (ALIGN_EPI) { if (wr == 0) PG8_BAR; }
	s_add_i32 s46, s70, s53
	v_lshl_add_u64 v[230:231], v[230:231], 0, s[14:15]
	s_mov_b32 m0, s46
	ds_read_b128 v[160:163], v198 offset:49152
	ds_read_b128 v[202:205], v198 offset:50176
	ds_read_b128 v[206:209], v198 offset:51200
	ds_read_b128 v[210:213], v198 offset:52224
	ds_read_b128 v[214:217], v198 offset:53248
	ds_read_b128 v[218:221], v198 offset:54272
	ds_read_b128 v[222:225], v198 offset:55296
	ds_read_b128 v[226:229], v198 offset:56320
	global_load_lds_dwordx4 v[230:231], off
	s_add_i32 m0, s46, 0x2000
	s_add_u32 s44, s44, 0x10080
	v_lshl_add_u64 v[230:231], v[232:233], 0, s[14:15]
	s_addc_u32 s45, s45, 0
	s_add_i32 s46, s71, s53
	global_load_lds_dwordx4 v[230:231], off
	v_lshl_add_u64 v[230:231], s[44:45], 0, v[166:167]
	s_mov_b32 m0, s46
	s_nop 0
	global_load_lds_dwordx4 v[230:231], off
	v_lshl_add_u64 v[230:231], s[44:45], 0, v[170:171]
	s_add_i32 m0, s46, 0x2000
	s_nop 0
	global_load_lds_dwordx4 v[230:231], off
	v_lshl_add_u64 v[230:231], v[234:235], 0, s[14:15]
	s_mov_b32 m0, s63
	s_nop 0
	global_load_lds_dwordx4 v[230:231], off
	v_lshl_add_u64 v[230:231], v[236:237], 0, s[14:15]
	s_mov_b32 m0, s64
	s_nop 0
	global_load_lds_dwordx4 v[230:231], off
	s_waitcnt vmcnt(8)
	s_waitcnt lgkmcnt(0)
	s_barrier
	s_setprio 1
	v_mfma_f32_16x16x32_bf16 v[60:63], v[128:131], v[160:163], v[60:63]
	v_mfma_f32_16x16x32_bf16 v[56:59], v[136:139], v[160:163], v[56:59]
	v_mfma_f32_16x16x32_bf16 v[44:47], v[128:131], v[206:209], v[44:47]
	v_mfma_f32_16x16x32_bf16 v[40:43], v[136:139], v[206:209], v[40:43]
	v_mfma_f32_16x16x32_bf16 v[28:31], v[128:131], v[214:217], v[28:31]
	v_mfma_f32_16x16x32_bf16 v[24:27], v[136:139], v[214:217], v[24:27]
	v_mfma_f32_16x16x32_bf16 v[12:15], v[128:131], v[222:225], v[12:15]
	v_mfma_f32_16x16x32_bf16 v[8:11], v[136:139], v[222:225], v[8:11]
	v_mfma_f32_16x16x32_bf16 v[60:63], v[132:135], v[202:205], v[60:63]
	v_mfma_f32_16x16x32_bf16 v[56:59], v[140:143], v[202:205], v[56:59]
	v_mfma_f32_16x16x32_bf16 v[44:47], v[132:135], v[210:213], v[44:47]
	v_mfma_f32_16x16x32_bf16 v[40:43], v[140:143], v[210:213], v[40:43]
	v_mfma_f32_16x16x32_bf16 v[28:31], v[132:135], v[218:221], v[28:31]
	v_mfma_f32_16x16x32_bf16 v[24:27], v[140:143], v[218:221], v[24:27]
	v_mfma_f32_16x16x32_bf16 v[12:15], v[132:135], v[226:229], v[12:15]
	v_mfma_f32_16x16x32_bf16 v[8:11], v[140:143], v[226:229], v[8:11]
	s_setprio 0
	s_setprio 1
	v_mfma_f32_16x16x32_bf16 v[52:55], v[144:147], v[160:163], v[52:55]
	v_mfma_f32_16x16x32_bf16 v[48:51], v[152:155], v[160:163], v[48:51]
	v_mfma_f32_16x16x32_bf16 v[36:39], v[144:147], v[206:209], v[36:39]
	v_mfma_f32_16x16x32_bf16 v[32:35], v[152:155], v[206:209], v[32:35]
	v_mfma_f32_16x16x32_bf16 v[20:23], v[144:147], v[214:217], v[20:23]
	v_mfma_f32_16x16x32_bf16 v[16:19], v[152:155], v[214:217], v[16:19]
	v_mfma_f32_16x16x32_bf16 v[4:7], v[144:147], v[222:225], v[4:7]
	v_mfma_f32_16x16x32_bf16 v[0:3], v[152:155], v[222:225], v[0:3]
	v_mfma_f32_16x16x32_bf16 v[52:55], v[148:151], v[202:205], v[52:55]
	v_mfma_f32_16x16x32_bf16 v[48:51], v[156:159], v[202:205], v[48:51]
	v_mfma_f32_16x16x32_bf16 v[36:39], v[148:151], v[210:213], v[36:39]
	v_mfma_f32_16x16x32_bf16 v[32:35], v[156:159], v[210:213], v[32:35]
	v_mfma_f32_16x16x32_bf16 v[20:23], v[148:151], v[218:221], v[20:23]
	v_mfma_f32_16x16x32_bf16 v[16:19], v[156:159], v[218:221], v[16:19]
	v_mfma_f32_16x16x32_bf16 v[4:7], v[148:151], v[226:229], v[4:7]
	v_mfma_f32_16x16x32_bf16 v[0:3], v[156:159], v[226:229], v[0:3]
	s_setprio 0
	s_barrier
	s_add_i32 s69, s69, 2
	s_add_u32 s10, s10, 0x100
	s_addc_u32 s11, s11, 0
	s_add_u32 s39, s39, 0x100
	s_addc_u32 s68, s68, 0
	s_cmp_gt_u32 s69, 13
	s_cbranch_scc0 .LBB0_219
	s_and_b64 vcc, exec, s[16:17]
	s_cbranch_vccz .LBB0_222
	s_barrier

; #define PG8_STAGE(bufoff, gbase, voff) do { _Pragma("unroll") for (int _i = 0; _i < 2; ++_i) \
;         __builtin_amdgcn_global_load_lds((const unsigned*)((const char*)(gbase) + (voff)[_i]), (PG8_LAS unsigned*)(lds + (bufoff) + ldsw + _i * 8192), 16, 0, 0); } while (0)
; #define PG8_LDA(dst, b, h) do { _Pragma("unroll") for (int m = 0; m < 4; ++m) _Pragma("unroll") for (int k = 0; k < 2; ++k) dst[m][k] = *(const PG8_LAS bf16x8*)(lds + PG8_SA(b, h) + aoff + m * 2048 + k * 1024); } while (0)
; #define PG8_LDB(dst, b, h) do { _Pragma("unroll") for (int n = 0; n < 2; ++n) _Pragma("unroll") for (int k = 0; k < 2; ++k) dst[n][k] = *(const PG8_LAS bf16x8*)(lds + PG8_SB(b, h) + boff + n * 2048 + k * 1024); } while (0)
; #define PG8_MMA(ai, bj, At, Bt) do { __builtin_amdgcn_s_setprio(1); _Pragma("unroll") for (int m = 0; m < 4; ++m) _Pragma("unroll") for (int n = 0; n < 2; ++n) _Pragma("unroll") for (int k = 0; k < 2; ++k) \
;         acc[ai][bj][m][n] = __builtin_amdgcn_mfma_f32_16x16x32_bf16(Bt[n][k], At[m][k], acc[ai][bj][m][n], 0, 0, 0); __builtin_amdgcn_s_setprio(0); } while (0)
; #define PG8_WAIT_V(n) asm volatile("s_waitcnt vmcnt(" #n ")" ::: "memory")
; #define PG8_WAIT_L(n) asm volatile("s_waitcnt lgkmcnt(" #n ")" ::: "memory")
; #define PG8_BAR __builtin_amdgcn_s_barrier()
; #define PG8_SCHED __builtin_amdgcn_sched_barrier(0)
; template <class Epi, class Sched, bool ALIGN_EPI = false, bool SP2 = false>
; __device__ __forceinline__ void gemm_phase(PG8_LAS unsigned char* lds, const Gemm g, const Sched& S, const Epi& E) {
;     ...
;             const char* a2 = last ? nA : cA + (size_t)(t + 2) * kstep; const char* b2 = last ? nB : cB + (size_t)(t + 2) * kstep;
;             const char* a3 = a2 + kstep; const char* b3 = b2 + kstep;
;             if (last && has_next) S.a_ready(nxt);
;             if constexpr (SP2) {
;             PG8_LDB(B0, 0, 0); PG8_LDB(B1, 0, 1); PG8_SCHED; PG8_LDA(At, 0, 0); PG8_STAGE(PG8_SA(1, 1), a1 + hstep, voffA);
;             PG8_WAIT_V(8); PG8_WAIT_L(0); PG8_BAR; PG8_MMA(0, 0, At, B0); PG8_MMA(0, 1, At, B1); PG8_BAR; PG8_SCHED;
;             PG8_LDA(At, 0, 1); PG8_STAGE(PG8_SB(0, 0), b2, voffB); PG8_STAGE(PG8_SB(0, 1), b2 + hstepB, voffB); PG8_STAGE(PG8_SA(0, 0), a2, voffA);
.LBB0_453:
	ds_read_b128 v[128:131], v178
	ds_read_b128 v[150:153], v178 offset:1024
	ds_read_b128 v[154:157], v178 offset:2048
	ds_read_b128 v[186:189], v178 offset:3072
	ds_read_b128 v[190:193], v179
	ds_read_b128 v[194:197], v179 offset:1024
	ds_read_b128 v[198:201], v179 offset:2048
	ds_read_b128 v[202:205], v179 offset:3072
	s_add_u32 s36, s0, 0xfffc0080
	s_addc_u32 s37, s1, -1
	s_cmp_eq_u32 s56, 12
	s_cselect_b32 s39, s29, s37
	s_cselect_b32 s38, s28, s36
	s_cselect_b32 s37, s25, s55
	s_cselect_b32 s36, s27, s54
	v_lshl_add_u64 v[238:239], s[0:1], 0, v[134:135]
	s_add_i32 m0, s35, 0xc000
	ds_read_b128 v[206:209], v180
	ds_read_b128 v[210:213], v180 offset:1024
	ds_read_b128 v[214:217], v180 offset:2048
	ds_read_b128 v[218:221], v180 offset:3072
	ds_read_b128 v[222:225], v180 offset:4096
	ds_read_b128 v[226:229], v180 offset:5120
	ds_read_b128 v[230:233], v180 offset:6144
	ds_read_b128 v[234:237], v180 offset:7168
	global_load_lds_dwordx4 v[238:239], off
	v_lshl_add_u64 v[238:239], s[0:1], 0, v[136:137]
	s_add_i32 m0, s35, 0xe000
	s_nop 0
	global_load_lds_dwordx4 v[238:239], off
	s_waitcnt vmcnt(8)
	s_waitcnt lgkmcnt(0)
	s_barrier
	s_setprio 1
	v_mfma_f32_16x16x32_bf16 v[124:127], v[128:131], v[206:209], v[124:127]
	v_mfma_f32_16x16x32_bf16 v[120:123], v[154:157], v[206:209], v[120:123]
	v_mfma_f32_16x16x32_bf16 v[116:119], v[128:131], v[214:217], v[116:119]
	v_mfma_f32_16x16x32_bf16 v[112:115], v[154:157], v[214:217], v[112:115]
	v_mfma_f32_16x16x32_bf16 v[92:95], v[128:131], v[222:225], v[92:95]
	v_mfma_f32_16x16x32_bf16 v[88:91], v[154:157], v[222:225], v[88:91]
	v_mfma_f32_16x16x32_bf16 v[76:79], v[128:131], v[230:233], v[76:79]
	v_mfma_f32_16x16x32_bf16 v[72:75], v[154:157], v[230:233], v[72:75]
	v_mfma_f32_16x16x32_bf16 v[124:127], v[150:153], v[210:213], v[124:127]
	v_mfma_f32_16x16x32_bf16 v[120:123], v[186:189], v[210:213], v[120:123]
	v_mfma_f32_16x16x32_bf16 v[116:119], v[150:153], v[218:221], v[116:119]
	v_mfma_f32_16x16x32_bf16 v[112:115], v[186:189], v[218:221], v[112:115]
	v_mfma_f32_16x16x32_bf16 v[92:95], v[150:153], v[226:229], v[92:95]
	v_mfma_f32_16x16x32_bf16 v[88:91], v[186:189], v[226:229], v[88:91]
	v_mfma_f32_16x16x32_bf16 v[76:79], v[150:153], v[234:237], v[76:79]
	v_mfma_f32_16x16x32_bf16 v[72:75], v[186:189], v[234:237], v[72:75]
	s_setprio 0
	s_setprio 1
	v_mfma_f32_16x16x32_bf16 v[108:111], v[190:193], v[206:209], v[108:111]
	v_mfma_f32_16x16x32_bf16 v[104:107], v[198:201], v[206:209], v[104:107]
	v_mfma_f32_16x16x32_bf16 v[100:103], v[190:193], v[214:217], v[100:103]
	v_mfma_f32_16x16x32_bf16 v[96:99], v[198:201], v[214:217], v[96:99]
	v_mfma_f32_16x16x32_bf16 v[84:87], v[190:193], v[222:225], v[84:87]
	v_mfma_f32_16x16x32_bf16 v[80:83], v[198:201], v[222:225], v[80:83]
	v_mfma_f32_16x16x32_bf16 v[68:71], v[190:193], v[230:233], v[68:71]
	v_mfma_f32_16x16x32_bf16 v[64:67], v[198:201], v[230:233], v[64:67]
	v_mfma_f32_16x16x32_bf16 v[108:111], v[194:197], v[210:213], v[108:111]
	v_mfma_f32_16x16x32_bf16 v[104:107], v[202:205], v[210:213], v[104:107]
	v_mfma_f32_16x16x32_bf16 v[100:103], v[194:197], v[218:221], v[100:103]
	v_mfma_f32_16x16x32_bf16 v[96:99], v[202:205], v[218:221], v[96:99]
	v_mfma_f32_16x16x32_bf16 v[84:87], v[194:197], v[226:229], v[84:87]
	v_mfma_f32_16x16x32_bf16 v[80:83], v[202:205], v[226:229], v[80:83]
	v_mfma_f32_16x16x32_bf16 v[68:71], v[194:197], v[234:237], v[68:71]
	v_mfma_f32_16x16x32_bf16 v[64:67], v[202:205], v[234:237], v[64:67]
	s_setprio 0
	s_barrier
	s_add_i32 s57, s51, s42
	v_lshl_add_u64 v[238:239], s[36:37], 0, v[162:163]
	s_mov_b32 m0, s57
	ds_read_b128 v[206:209], v180 offset:16384
	ds_read_b128 v[210:213], v180 offset:17408
	ds_read_b128 v[214:217], v180 offset:18432
	ds_read_b128 v[218:221], v180 offset:19456
	ds_read_b128 v[222:225], v180 offset:20480
	ds_read_b128 v[226:229], v180 offset:21504
	ds_read_b128 v[230:233], v180 offset:22528
	ds_read_b128 v[234:237], v180 offset:23552
	global_load_lds_dwordx4 v[238:239], off
	s_add_i32 m0, s57, 0x2000
	s_add_u32 s58, s36, 0x10000
	v_lshl_add_u64 v[240:241], s[36:37], 0, v[166:167]
	s_addc_u32 s59, s37, 0
	s_add_i32 s57, s52, s42
	global_load_lds_dwordx4 v[240:241], off
	v_lshl_add_u64 v[242:243], s[58:59], 0, v[162:163]
	s_mov_b32 m0, s57
	v_lshl_add_u64 v[244:245], s[38:39], 0, v[164:165]
	global_load_lds_dwordx4 v[242:243], off
	v_lshl_add_u64 v[242:243], s[58:59], 0, v[166:167]
	s_add_i32 m0, s57, 0x2000
	s_nop 0
	global_load_lds_dwordx4 v[242:243], off
	v_lshl_add_u64 v[242:243], s[38:39], 0, v[160:161]
	s_mov_b32 m0, s35
	s_nop 0
	global_load_lds_dwordx4 v[242:243], off
	s_mov_b32 m0, s43
	s_nop 0
	global_load_lds_dwordx4 v[244:245], off
	s_waitcnt vmcnt(8)
	s_waitcnt lgkmcnt(0)
	s_barrier
; #define PG8_STAGE(bufoff, gbase, voff) do { _Pragma("unroll") for (int _i = 0; _i < 2; ++_i) \
;         __builtin_amdgcn_global_load_lds((const unsigned*)((const char*)(gbase) + (voff)[_i]), (PG8_LAS unsigned*)(lds + (bufoff) + ldsw + _i * 8192), 16, 0, 0); } while (0)
; #define PG8_LDA(dst, b, h) do { _Pragma("unroll") for (int m = 0; m < 4; ++m) _Pragma("unroll") for (int k = 0; k < 2; ++k) dst[m][k] = *(const PG8_LAS bf16x8*)(lds + PG8_SA(b, h) + aoff + m * 2048 + k * 1024); } while (0)
; #define PG8_LDB(dst, b, h) do { _Pragma("unroll") for (int n = 0; n < 2; ++n) _Pragma("unroll") for (int k = 0; k < 2; ++k) dst[n][k] = *(const PG8_LAS bf16x8*)(lds + PG8_SB(b, h) + boff + n * 2048 + k * 1024); } while (0)
; #define PG8_MMA(ai, bj, At, Bt) do { __builtin_amdgcn_s_setprio(1); _Pragma("unroll") for (int m = 0; m < 4; ++m) _Pragma("unroll") for (int n = 0; n < 2; ++n) _Pragma("unroll") for (int k = 0; k < 2; ++k) \
;         acc[ai][bj][m][n] = __builtin_amdgcn_mfma_f32_16x16x32_bf16(Bt[n][k], At[m][k], acc[ai][bj][m][n], 0, 0, 0); __builtin_amdgcn_s_setprio(0); } while (0)
; #define PG8_WAIT_V(n) asm volatile("s_waitcnt vmcnt(" #n ")" ::: "memory")
; #define PG8_WAIT_L(n) asm volatile("s_waitcnt lgkmcnt(" #n ")" ::: "memory")
; #define PG8_BAR __builtin_amdgcn_s_barrier()
; #define PG8_SCHED __builtin_amdgcn_sched_barrier(0)
; template <class Epi, class Sched, bool ALIGN_EPI = false, bool SP2 = false>
; __device__ __forceinline__ void gemm_phase(PG8_LAS unsigned char* lds, const Gemm g, const Sched& S, const Epi& E) {
;     ...
;             PG8_WAIT_V(8); PG8_WAIT_L(0); PG8_BAR; PG8_MMA(1, 0, At, B0); PG8_MMA(1, 1, At, B1); PG8_BAR; PG8_SCHED;
;             PG8_LDB(B0, 1, 0); PG8_LDB(B1, 1, 1); PG8_SCHED; PG8_LDA(At, 1, 0); PG8_STAGE(PG8_SA(0, 1), a2 + hstep, voffA);
;             PG8_WAIT_V(8); PG8_WAIT_L(0); PG8_BAR; PG8_MMA(0, 0, At, B0); PG8_MMA(0, 1, At, B1); PG8_BAR; PG8_SCHED;
	s_setprio 1
	v_mfma_f32_16x16x32_bf16 v[60:63], v[128:131], v[206:209], v[60:63]
	v_mfma_f32_16x16x32_bf16 v[56:59], v[154:157], v[206:209], v[56:59]
	v_mfma_f32_16x16x32_bf16 v[44:47], v[128:131], v[214:217], v[44:47]
	v_mfma_f32_16x16x32_bf16 v[40:43], v[154:157], v[214:217], v[40:43]
	v_mfma_f32_16x16x32_bf16 v[28:31], v[128:131], v[222:225], v[28:31]
	v_mfma_f32_16x16x32_bf16 v[24:27], v[154:157], v[222:225], v[24:27]
	v_mfma_f32_16x16x32_bf16 v[12:15], v[128:131], v[230:233], v[12:15]
	v_mfma_f32_16x16x32_bf16 v[8:11], v[154:157], v[230:233], v[8:11]
	v_mfma_f32_16x16x32_bf16 v[60:63], v[150:153], v[210:213], v[60:63]
	v_mfma_f32_16x16x32_bf16 v[56:59], v[186:189], v[210:213], v[56:59]
	v_mfma_f32_16x16x32_bf16 v[44:47], v[150:153], v[218:221], v[44:47]
	v_mfma_f32_16x16x32_bf16 v[40:43], v[186:189], v[218:221], v[40:43]
	v_mfma_f32_16x16x32_bf16 v[28:31], v[150:153], v[226:229], v[28:31]
	v_mfma_f32_16x16x32_bf16 v[24:27], v[186:189], v[226:229], v[24:27]
	v_mfma_f32_16x16x32_bf16 v[12:15], v[150:153], v[234:237], v[12:15]
	v_mfma_f32_16x16x32_bf16 v[8:11], v[186:189], v[234:237], v[8:11]
	s_setprio 0
	s_setprio 1
	v_mfma_f32_16x16x32_bf16 v[52:55], v[190:193], v[206:209], v[52:55]
	v_mfma_f32_16x16x32_bf16 v[48:51], v[198:201], v[206:209], v[48:51]
	v_mfma_f32_16x16x32_bf16 v[36:39], v[190:193], v[214:217], v[36:39]
	v_mfma_f32_16x16x32_bf16 v[32:35], v[198:201], v[214:217], v[32:35]
	v_mfma_f32_16x16x32_bf16 v[20:23], v[190:193], v[222:225], v[20:23]
	v_mfma_f32_16x16x32_bf16 v[16:19], v[198:201], v[222:225], v[16:19]
	v_mfma_f32_16x16x32_bf16 v[4:7], v[190:193], v[230:233], v[4:7]
	v_mfma_f32_16x16x32_bf16 v[0:3], v[198:201], v[230:233], v[0:3]
	v_mfma_f32_16x16x32_bf16 v[52:55], v[194:197], v[210:213], v[52:55]
	v_mfma_f32_16x16x32_bf16 v[48:51], v[202:205], v[210:213], v[48:51]
	v_mfma_f32_16x16x32_bf16 v[36:39], v[194:197], v[218:221], v[36:39]
	v_mfma_f32_16x16x32_bf16 v[32:35], v[202:205], v[218:221], v[32:35]
	v_mfma_f32_16x16x32_bf16 v[20:23], v[194:197], v[226:229], v[20:23]
	v_mfma_f32_16x16x32_bf16 v[16:19], v[202:205], v[226:229], v[16:19]
	v_mfma_f32_16x16x32_bf16 v[4:7], v[194:197], v[234:237], v[4:7]
	v_mfma_f32_16x16x32_bf16 v[0:3], v[202:205], v[234:237], v[0:3]
	s_setprio 0
	s_barrier
	s_add_i32 s57, 0, 0x18000
	v_add_u32_e32 v147, s57, v174
	s_add_i32 s58, 0, 0x1c000
	ds_read_b128 v[128:131], v147
	ds_read_b128 v[150:153], v147 offset:1024
	ds_read_b128 v[154:157], v147 offset:2048
	ds_read_b128 v[186:189], v147 offset:3072
	v_add_u32_e32 v147, s58, v174
	ds_read_b128 v[190:193], v147
	ds_read_b128 v[194:197], v147 offset:1024
	ds_read_b128 v[198:201], v147 offset:2048
	ds_read_b128 v[202:205], v147 offset:3072
	s_add_u32 s38, s38, 0x40000
	s_addc_u32 s39, s39, 0
	s_mov_b32 m0, s44
	v_lshl_add_u64 v[246:247], s[38:39], 0, v[160:161]
	ds_read_b128 v[206:209], v180 offset:32768
	ds_read_b128 v[210:213], v180 offset:33792
	ds_read_b128 v[214:217], v180 offset:34816
	ds_read_b128 v[218:221], v180 offset:35840
	ds_read_b128 v[222:225], v180 offset:36864
	ds_read_b128 v[226:229], v180 offset:37888
	ds_read_b128 v[230:233], v180 offset:38912
	ds_read_b128 v[234:237], v180 offset:39936
	global_load_lds_dwordx4 v[246:247], off
	v_lshl_add_u64 v[246:247], s[38:39], 0, v[164:165]
	s_mov_b32 m0, s45
	s_nop 0
	global_load_lds_dwordx4 v[246:247], off
	s_waitcnt vmcnt(8)
	s_waitcnt lgkmcnt(0)
	s_barrier
	s_setprio 1
	v_mfma_f32_16x16x32_bf16 v[124:127], v[128:131], v[206:209], v[124:127]
	v_mfma_f32_16x16x32_bf16 v[120:123], v[154:157], v[206:209], v[120:123]
	v_mfma_f32_16x16x32_bf16 v[116:119], v[128:131], v[214:217], v[116:119]
	v_mfma_f32_16x16x32_bf16 v[112:115], v[154:157], v[214:217], v[112:115]
	v_mfma_f32_16x16x32_bf16 v[92:95], v[128:131], v[222:225], v[92:95]
	v_mfma_f32_16x16x32_bf16 v[88:91], v[154:157], v[222:225], v[88:91]
	v_mfma_f32_16x16x32_bf16 v[76:79], v[128:131], v[230:233], v[76:79]
	v_mfma_f32_16x16x32_bf16 v[72:75], v[154:157], v[230:233], v[72:75]
	v_mfma_f32_16x16x32_bf16 v[124:127], v[150:153], v[210:213], v[124:127]
	v_mfma_f32_16x16x32_bf16 v[120:123], v[186:189], v[210:213], v[120:123]
	v_mfma_f32_16x16x32_bf16 v[116:119], v[150:153], v[218:221], v[116:119]
	v_mfma_f32_16x16x32_bf16 v[112:115], v[186:189], v[218:221], v[112:115]
	v_mfma_f32_16x16x32_bf16 v[92:95], v[150:153], v[226:229], v[92:95]
	v_mfma_f32_16x16x32_bf16 v[88:91], v[186:189], v[226:229], v[88:91]
	v_mfma_f32_16x16x32_bf16 v[76:79], v[150:153], v[234:237], v[76:79]
	v_mfma_f32_16x16x32_bf16 v[72:75], v[186:189], v[234:237], v[72:75]
	s_setprio 0
	s_setprio 1
	v_mfma_f32_16x16x32_bf16 v[108:111], v[190:193], v[206:209], v[108:111]
	v_mfma_f32_16x16x32_bf16 v[104:107], v[198:201], v[206:209], v[104:107]
	v_mfma_f32_16x16x32_bf16 v[100:103], v[190:193], v[214:217], v[100:103]
	v_mfma_f32_16x16x32_bf16 v[96:99], v[198:201], v[214:217], v[96:99]
	v_mfma_f32_16x16x32_bf16 v[84:87], v[190:193], v[222:225], v[84:87]
	v_mfma_f32_16x16x32_bf16 v[80:83], v[198:201], v[222:225], v[80:83]
	v_mfma_f32_16x16x32_bf16 v[68:71], v[190:193], v[230:233], v[68:71]
	v_mfma_f32_16x16x32_bf16 v[64:67], v[198:201], v[230:233], v[64:67]
	v_mfma_f32_16x16x32_bf16 v[108:111], v[194:197], v[210:213], v[108:111]
	v_mfma_f32_16x16x32_bf16 v[104:107], v[202:205], v[210:213], v[104:107]
	v_mfma_f32_16x16x32_bf16 v[100:103], v[194:197], v[218:221], v[100:103]
	v_mfma_f32_16x16x32_bf16 v[96:99], v[202:205], v[218:221], v[96:99]
	v_mfma_f32_16x16x32_bf16 v[84:87], v[194:197], v[226:229], v[84:87]
	v_mfma_f32_16x16x32_bf16 v[80:83], v[202:205], v[226:229], v[80:83]
	v_mfma_f32_16x16x32_bf16 v[68:71], v[194:197], v[234:237], v[68:71]
	v_mfma_f32_16x16x32_bf16 v[64:67], v[202:205], v[234:237], v[64:67]
	s_setprio 0
	s_barrier
; #define PG8_STAGE(bufoff, gbase, voff) do { _Pragma("unroll") for (int _i = 0; _i < 2; ++_i) \
;         __builtin_amdgcn_global_load_lds((const unsigned*)((const char*)(gbase) + (voff)[_i]), (PG8_LAS unsigned*)(lds + (bufoff) + ldsw + _i * 8192), 16, 0, 0); } while (0)
; #define PG8_LDA(dst, b, h) do { _Pragma("unroll") for (int m = 0; m < 4; ++m) _Pragma("unroll") for (int k = 0; k < 2; ++k) dst[m][k] = *(const PG8_LAS bf16x8*)(lds + PG8_SA(b, h) + aoff + m * 2048 + k * 1024); } while (0)
; #define PG8_MMA(ai, bj, At, Bt) do { __builtin_amdgcn_s_setprio(1); _Pragma("unroll") for (int m = 0; m < 4; ++m) _Pragma("unroll") for (int n = 0; n < 2; ++n) _Pragma("unroll") for (int k = 0; k < 2; ++k) \
;         acc[ai][bj][m][n] = __builtin_amdgcn_mfma_f32_16x16x32_bf16(Bt[n][k], At[m][k], acc[ai][bj][m][n], 0, 0, 0); __builtin_amdgcn_s_setprio(0); } while (0)
; #define PG8_WAIT_V(n) asm volatile("s_waitcnt vmcnt(" #n ")" ::: "memory")
; #define PG8_WAIT_L(n) asm volatile("s_waitcnt lgkmcnt(" #n ")" ::: "memory")
; #define PG8_BAR __builtin_amdgcn_s_barrier()
; #define PG8_SCHED __builtin_amdgcn_sched_barrier(0)
; template <class Epi, class Sched, bool ALIGN_EPI = false, bool SP2 = false>
; __device__ __forceinline__ void gemm_phase(PG8_LAS unsigned char* lds, const Gemm g, const Sched& S, const Epi& E) {
;     ...
;             PG8_LDA(At, 1, 1); PG8_STAGE(PG8_SB(1, 0), b3, voffB); PG8_STAGE(PG8_SB(1, 1), b3 + hstepB, voffB); PG8_STAGE(PG8_SA(1, 0), a3, voffA);
;             PG8_WAIT_V(8); PG8_WAIT_L(0); PG8_BAR; PG8_MMA(1, 0, At, B0); PG8_MMA(1, 1, At, B1); PG8_BAR; PG8_SCHED;
;     ...
;         if constexpr (ALIGN_EPI) { if (wr == 0) PG8_BAR; }
	s_add_i32 s38, s57, s42
	v_lshl_add_u64 v[238:239], v[238:239], 0, s[14:15]
	s_mov_b32 m0, s38
	ds_read_b128 v[206:209], v180 offset:49152
	ds_read_b128 v[210:213], v180 offset:50176
	ds_read_b128 v[214:217], v180 offset:51200
	ds_read_b128 v[218:221], v180 offset:52224
	ds_read_b128 v[222:225], v180 offset:53248
	ds_read_b128 v[226:229], v180 offset:54272
	ds_read_b128 v[230:233], v180 offset:55296
	ds_read_b128 v[234:237], v180 offset:56320
	global_load_lds_dwordx4 v[238:239], off
	s_add_i32 m0, s38, 0x2000
	s_add_u32 s36, s36, 0x10080
	v_lshl_add_u64 v[238:239], v[240:241], 0, s[14:15]
	s_addc_u32 s37, s37, 0
	s_add_i32 s38, s58, s42
	global_load_lds_dwordx4 v[238:239], off
	v_lshl_add_u64 v[238:239], s[36:37], 0, v[162:163]
	s_mov_b32 m0, s38
	s_nop 0
	global_load_lds_dwordx4 v[238:239], off
	v_lshl_add_u64 v[238:239], s[36:37], 0, v[166:167]
	s_add_i32 m0, s38, 0x2000
	s_nop 0
	global_load_lds_dwordx4 v[238:239], off
	v_lshl_add_u64 v[238:239], v[242:243], 0, s[14:15]
	s_mov_b32 m0, s47
	s_nop 0
	global_load_lds_dwordx4 v[238:239], off
	v_lshl_add_u64 v[238:239], v[244:245], 0, s[14:15]
	s_mov_b32 m0, s48
	s_nop 0
	global_load_lds_dwordx4 v[238:239], off
	s_waitcnt vmcnt(8)
	s_waitcnt lgkmcnt(0)
	s_barrier
	s_setprio 1
	v_mfma_f32_16x16x32_bf16 v[60:63], v[128:131], v[206:209], v[60:63]
	v_mfma_f32_16x16x32_bf16 v[56:59], v[154:157], v[206:209], v[56:59]
	v_mfma_f32_16x16x32_bf16 v[44:47], v[128:131], v[214:217], v[44:47]
	v_mfma_f32_16x16x32_bf16 v[40:43], v[154:157], v[214:217], v[40:43]
	v_mfma_f32_16x16x32_bf16 v[28:31], v[128:131], v[222:225], v[28:31]
	v_mfma_f32_16x16x32_bf16 v[24:27], v[154:157], v[222:225], v[24:27]
	v_mfma_f32_16x16x32_bf16 v[12:15], v[128:131], v[230:233], v[12:15]
	v_mfma_f32_16x16x32_bf16 v[8:11], v[154:157], v[230:233], v[8:11]
	v_mfma_f32_16x16x32_bf16 v[60:63], v[150:153], v[210:213], v[60:63]
	v_mfma_f32_16x16x32_bf16 v[56:59], v[186:189], v[210:213], v[56:59]
	v_mfma_f32_16x16x32_bf16 v[44:47], v[150:153], v[218:221], v[44:47]
	v_mfma_f32_16x16x32_bf16 v[40:43], v[186:189], v[218:221], v[40:43]
	v_mfma_f32_16x16x32_bf16 v[28:31], v[150:153], v[226:229], v[28:31]
	v_mfma_f32_16x16x32_bf16 v[24:27], v[186:189], v[226:229], v[24:27]
	v_mfma_f32_16x16x32_bf16 v[12:15], v[150:153], v[234:237], v[12:15]
	v_mfma_f32_16x16x32_bf16 v[8:11], v[186:189], v[234:237], v[8:11]
	s_setprio 0
	s_setprio 1
	v_mfma_f32_16x16x32_bf16 v[52:55], v[190:193], v[206:209], v[52:55]
	v_mfma_f32_16x16x32_bf16 v[48:51], v[198:201], v[206:209], v[48:51]
	v_mfma_f32_16x16x32_bf16 v[36:39], v[190:193], v[214:217], v[36:39]
	v_mfma_f32_16x16x32_bf16 v[32:35], v[198:201], v[214:217], v[32:35]
	v_mfma_f32_16x16x32_bf16 v[20:23], v[190:193], v[222:225], v[20:23]
	v_mfma_f32_16x16x32_bf16 v[16:19], v[198:201], v[222:225], v[16:19]
	v_mfma_f32_16x16x32_bf16 v[4:7], v[190:193], v[230:233], v[4:7]
	v_mfma_f32_16x16x32_bf16 v[0:3], v[198:201], v[230:233], v[0:3]
	v_mfma_f32_16x16x32_bf16 v[52:55], v[194:197], v[210:213], v[52:55]
	v_mfma_f32_16x16x32_bf16 v[48:51], v[202:205], v[210:213], v[48:51]
	v_mfma_f32_16x16x32_bf16 v[36:39], v[194:197], v[218:221], v[36:39]
	v_mfma_f32_16x16x32_bf16 v[32:35], v[202:205], v[218:221], v[32:35]
	v_mfma_f32_16x16x32_bf16 v[20:23], v[194:197], v[226:229], v[20:23]
	v_mfma_f32_16x16x32_bf16 v[16:19], v[202:205], v[226:229], v[16:19]
	v_mfma_f32_16x16x32_bf16 v[4:7], v[194:197], v[234:237], v[4:7]
	v_mfma_f32_16x16x32_bf16 v[0:3], v[202:205], v[234:237], v[0:3]
	s_setprio 0
	s_barrier
	s_add_i32 s56, s56, 2
	s_add_u32 s0, s0, 0x100
	s_addc_u32 s1, s1, 0
	s_add_u32 s54, s54, 0x100
	s_addc_u32 s55, s55, 0
	s_cmp_gt_u32 s56, 13
	s_cbranch_scc0 .LBB0_453
	s_and_b64 vcc, exec, s[16:17]
	s_cbranch_vccz .LBB0_456
	s_barrier

; #define PG8_STAGE(bufoff, gbase, voff) do { _Pragma("unroll") for (int _i = 0; _i < 2; ++_i) \
;         __builtin_amdgcn_global_load_lds((const unsigned*)((const char*)(gbase) + (voff)[_i]), (PG8_LAS unsigned*)(lds + (bufoff) + ldsw + _i * 8192), 16, 0, 0); } while (0)
; #define PG8_LDA(dst, b, h) do { _Pragma("unroll") for (int m = 0; m < 4; ++m) _Pragma("unroll") for (int k = 0; k < 2; ++k) dst[m][k] = *(const PG8_LAS bf16x8*)(lds + PG8_SA(b, h) + aoff + m * 2048 + k * 1024); } while (0)
; #define PG8_LDB(dst, b, h) do { _Pragma("unroll") for (int n = 0; n < 2; ++n) _Pragma("unroll") for (int k = 0; k < 2; ++k) dst[n][k] = *(const PG8_LAS bf16x8*)(lds + PG8_SB(b, h) + boff + n * 2048 + k * 1024); } while (0)
; #define PG8_MMA(ai, bj, At, Bt) do { __builtin_amdgcn_s_setprio(1); _Pragma("unroll") for (int m = 0; m < 4; ++m) _Pragma("unroll") for (int n = 0; n < 2; ++n) _Pragma("unroll") for (int k = 0; k < 2; ++k) \
;         acc[ai][bj][m][n] = __builtin_amdgcn_mfma_f32_16x16x32_bf16(Bt[n][k], At[m][k], acc[ai][bj][m][n], 0, 0, 0); __builtin_amdgcn_s_setprio(0); } while (0)
; #define PG8_WAIT_V(n) asm volatile("s_waitcnt vmcnt(" #n ")" ::: "memory")
; #define PG8_WAIT_L(n) asm volatile("s_waitcnt lgkmcnt(" #n ")" ::: "memory")
; #define PG8_BAR __builtin_amdgcn_s_barrier()
; #define PG8_SCHED __builtin_amdgcn_sched_barrier(0)
; template <class Epi, class Sched, bool ALIGN_EPI = false, bool SP2 = false>
; __device__ __forceinline__ void gemm_phase(PG8_LAS unsigned char* lds, const Gemm g, const Sched& S, const Epi& E) {
;     ...
;             const char* a2 = last ? nA : cA + (size_t)(t + 2) * kstep; const char* b2 = last ? nB : cB + (size_t)(t + 2) * kstep;
;             const char* a3 = a2 + kstep; const char* b3 = b2 + kstep;
;             if (last && has_next) S.a_ready(nxt);
;             if constexpr (SP2) {
;             PG8_LDB(B0, 0, 0); PG8_LDB(B1, 0, 1); PG8_SCHED; PG8_LDA(At, 0, 0); PG8_STAGE(PG8_SA(1, 1), a1 + hstep, voffA);
;             PG8_WAIT_V(8); PG8_WAIT_L(0); PG8_BAR; PG8_MMA(0, 0, At, B0); PG8_MMA(0, 1, At, B1); PG8_BAR; PG8_SCHED;
;             PG8_LDA(At, 0, 1); PG8_STAGE(PG8_SB(0, 0), b2, voffB); PG8_STAGE(PG8_SB(0, 1), b2 + hstepB, voffB); PG8_STAGE(PG8_SA(0, 0), a2, voffA);
.LBB0_479:
	ds_read_b128 v[128:131], v201
	ds_read_b128 v[132:135], v201 offset:1024
	ds_read_b128 v[136:139], v201 offset:2048
	ds_read_b128 v[140:143], v201 offset:3072
	ds_read_b128 v[144:147], v202
	ds_read_b128 v[148:151], v202 offset:1024
	ds_read_b128 v[152:155], v202 offset:2048
	ds_read_b128 v[156:159], v202 offset:3072
	s_add_u32 s28, s0, 0xfffc0080
	s_addc_u32 s29, s1, -1
	s_cmp_eq_u32 s52, 12
	s_cselect_b32 s31, s23, s29
	s_cselect_b32 s30, s22, s28
	s_cselect_b32 s29, s19, s51
	s_cselect_b32 s28, s21, s50
	v_lshl_add_u64 v[196:197], s[0:1], 0, v[170:171]
	s_add_i32 m0, s27, 0xc000
	ds_read_b128 v[188:191], v203
	ds_read_b128 v[192:195], v203 offset:1024
	ds_read_b128 v[206:209], v203 offset:2048
	ds_read_b128 v[210:213], v203 offset:3072
	ds_read_b128 v[214:217], v203 offset:4096
	ds_read_b128 v[218:221], v203 offset:5120
	ds_read_b128 v[222:225], v203 offset:6144
	ds_read_b128 v[226:229], v203 offset:7168
	global_load_lds_dwordx4 v[196:197], off
	v_lshl_add_u64 v[196:197], s[0:1], 0, v[172:173]
	s_add_i32 m0, s27, 0xe000
	s_nop 0
	global_load_lds_dwordx4 v[196:197], off
	s_waitcnt vmcnt(8)
	s_waitcnt lgkmcnt(0)
	s_barrier
	s_setprio 1
	v_mfma_f32_16x16x32_bf16 v[124:127], v[128:131], v[188:191], v[124:127]
	v_mfma_f32_16x16x32_bf16 v[120:123], v[136:139], v[188:191], v[120:123]
	v_mfma_f32_16x16x32_bf16 v[108:111], v[128:131], v[206:209], v[108:111]
	v_mfma_f32_16x16x32_bf16 v[104:107], v[136:139], v[206:209], v[104:107]
	v_mfma_f32_16x16x32_bf16 v[92:95], v[128:131], v[214:217], v[92:95]
	v_mfma_f32_16x16x32_bf16 v[88:91], v[136:139], v[214:217], v[88:91]
	v_mfma_f32_16x16x32_bf16 v[76:79], v[128:131], v[222:225], v[76:79]
	v_mfma_f32_16x16x32_bf16 v[72:75], v[136:139], v[222:225], v[72:75]
	v_mfma_f32_16x16x32_bf16 v[124:127], v[132:135], v[192:195], v[124:127]
	v_mfma_f32_16x16x32_bf16 v[120:123], v[140:143], v[192:195], v[120:123]
	v_mfma_f32_16x16x32_bf16 v[108:111], v[132:135], v[210:213], v[108:111]
	v_mfma_f32_16x16x32_bf16 v[104:107], v[140:143], v[210:213], v[104:107]
	v_mfma_f32_16x16x32_bf16 v[92:95], v[132:135], v[218:221], v[92:95]
	v_mfma_f32_16x16x32_bf16 v[88:91], v[140:143], v[218:221], v[88:91]
	v_mfma_f32_16x16x32_bf16 v[76:79], v[132:135], v[226:229], v[76:79]
	v_mfma_f32_16x16x32_bf16 v[72:75], v[140:143], v[226:229], v[72:75]
	s_setprio 0
	s_setprio 1
	v_mfma_f32_16x16x32_bf16 v[116:119], v[144:147], v[188:191], v[116:119]
	v_mfma_f32_16x16x32_bf16 v[112:115], v[152:155], v[188:191], v[112:115]
	v_mfma_f32_16x16x32_bf16 v[100:103], v[144:147], v[206:209], v[100:103]
	v_mfma_f32_16x16x32_bf16 v[96:99], v[152:155], v[206:209], v[96:99]
	v_mfma_f32_16x16x32_bf16 v[84:87], v[144:147], v[214:217], v[84:87]
	v_mfma_f32_16x16x32_bf16 v[80:83], v[152:155], v[214:217], v[80:83]
	v_mfma_f32_16x16x32_bf16 v[68:71], v[144:147], v[222:225], v[68:71]
	v_mfma_f32_16x16x32_bf16 v[64:67], v[152:155], v[222:225], v[64:67]
	v_mfma_f32_16x16x32_bf16 v[116:119], v[148:151], v[192:195], v[116:119]
	v_mfma_f32_16x16x32_bf16 v[112:115], v[156:159], v[192:195], v[112:115]
	v_mfma_f32_16x16x32_bf16 v[100:103], v[148:151], v[210:213], v[100:103]
	v_mfma_f32_16x16x32_bf16 v[96:99], v[156:159], v[210:213], v[96:99]
	v_mfma_f32_16x16x32_bf16 v[84:87], v[148:151], v[218:221], v[84:87]
	v_mfma_f32_16x16x32_bf16 v[80:83], v[156:159], v[218:221], v[80:83]
	v_mfma_f32_16x16x32_bf16 v[68:71], v[148:151], v[226:229], v[68:71]
	v_mfma_f32_16x16x32_bf16 v[64:67], v[156:159], v[226:229], v[64:67]
	s_setprio 0
	s_barrier
	s_add_i32 s53, s47, s38
	v_lshl_add_u64 v[196:197], s[28:29], 0, v[162:163]
	s_mov_b32 m0, s53
	ds_read_b128 v[188:191], v203 offset:16384
	ds_read_b128 v[192:195], v203 offset:17408
	ds_read_b128 v[206:209], v203 offset:18432
	ds_read_b128 v[210:213], v203 offset:19456
	ds_read_b128 v[214:217], v203 offset:20480
	ds_read_b128 v[218:221], v203 offset:21504
	ds_read_b128 v[222:225], v203 offset:22528
	ds_read_b128 v[226:229], v203 offset:23552
	global_load_lds_dwordx4 v[196:197], off
	s_add_i32 m0, s53, 0x2000
	s_add_u32 s54, s28, 0x10000
	v_lshl_add_u64 v[230:231], s[28:29], 0, v[166:167]
	s_addc_u32 s55, s29, 0
	s_add_i32 s53, s48, s38
	global_load_lds_dwordx4 v[230:231], off
	v_lshl_add_u64 v[232:233], s[54:55], 0, v[162:163]
	s_mov_b32 m0, s53
	v_lshl_add_u64 v[234:235], s[30:31], 0, v[164:165]
	global_load_lds_dwordx4 v[232:233], off
	v_lshl_add_u64 v[232:233], s[54:55], 0, v[166:167]
	s_add_i32 m0, s53, 0x2000
	s_nop 0
	global_load_lds_dwordx4 v[232:233], off
	v_lshl_add_u64 v[232:233], s[30:31], 0, v[160:161]
	s_mov_b32 m0, s27
	s_nop 0
	global_load_lds_dwordx4 v[232:233], off
	s_mov_b32 m0, s39
	s_nop 0
	global_load_lds_dwordx4 v[234:235], off
	s_waitcnt vmcnt(8)
	s_waitcnt lgkmcnt(0)
	s_barrier
; #define PG8_STAGE(bufoff, gbase, voff) do { _Pragma("unroll") for (int _i = 0; _i < 2; ++_i) \
;         __builtin_amdgcn_global_load_lds((const unsigned*)((const char*)(gbase) + (voff)[_i]), (PG8_LAS unsigned*)(lds + (bufoff) + ldsw + _i * 8192), 16, 0, 0); } while (0)
; #define PG8_LDA(dst, b, h) do { _Pragma("unroll") for (int m = 0; m < 4; ++m) _Pragma("unroll") for (int k = 0; k < 2; ++k) dst[m][k] = *(const PG8_LAS bf16x8*)(lds + PG8_SA(b, h) + aoff + m * 2048 + k * 1024); } while (0)
; #define PG8_LDB(dst, b, h) do { _Pragma("unroll") for (int n = 0; n < 2; ++n) _Pragma("unroll") for (int k = 0; k < 2; ++k) dst[n][k] = *(const PG8_LAS bf16x8*)(lds + PG8_SB(b, h) + boff + n * 2048 + k * 1024); } while (0)
; #define PG8_MMA(ai, bj, At, Bt) do { __builtin_amdgcn_s_setprio(1); _Pragma("unroll") for (int m = 0; m < 4; ++m) _Pragma("unroll") for (int n = 0; n < 2; ++n) _Pragma("unroll") for (int k = 0; k < 2; ++k) \
;         acc[ai][bj][m][n] = __builtin_amdgcn_mfma_f32_16x16x32_bf16(Bt[n][k], At[m][k], acc[ai][bj][m][n], 0, 0, 0); __builtin_amdgcn_s_setprio(0); } while (0)
; #define PG8_WAIT_V(n) asm volatile("s_waitcnt vmcnt(" #n ")" ::: "memory")
; #define PG8_WAIT_L(n) asm volatile("s_waitcnt lgkmcnt(" #n ")" ::: "memory")
; #define PG8_BAR __builtin_amdgcn_s_barrier()
; #define PG8_SCHED __builtin_amdgcn_sched_barrier(0)
; template <class Epi, class Sched, bool ALIGN_EPI = false, bool SP2 = false>
; __device__ __forceinline__ void gemm_phase(PG8_LAS unsigned char* lds, const Gemm g, const Sched& S, const Epi& E) {
;     ...
;             PG8_WAIT_V(8); PG8_WAIT_L(0); PG8_BAR; PG8_MMA(1, 0, At, B0); PG8_MMA(1, 1, At, B1); PG8_BAR; PG8_SCHED;
;             PG8_LDB(B0, 1, 0); PG8_LDB(B1, 1, 1); PG8_SCHED; PG8_LDA(At, 1, 0); PG8_STAGE(PG8_SA(0, 1), a2 + hstep, voffA);
;             PG8_WAIT_V(8); PG8_WAIT_L(0); PG8_BAR; PG8_MMA(0, 0, At, B0); PG8_MMA(0, 1, At, B1); PG8_BAR; PG8_SCHED;
	s_setprio 1
	v_mfma_f32_16x16x32_bf16 v[60:63], v[128:131], v[188:191], v[60:63]
	v_mfma_f32_16x16x32_bf16 v[56:59], v[136:139], v[188:191], v[56:59]
	v_mfma_f32_16x16x32_bf16 v[44:47], v[128:131], v[206:209], v[44:47]
	v_mfma_f32_16x16x32_bf16 v[40:43], v[136:139], v[206:209], v[40:43]
	v_mfma_f32_16x16x32_bf16 v[28:31], v[128:131], v[214:217], v[28:31]
	v_mfma_f32_16x16x32_bf16 v[24:27], v[136:139], v[214:217], v[24:27]
	v_mfma_f32_16x16x32_bf16 v[12:15], v[128:131], v[222:225], v[12:15]
	v_mfma_f32_16x16x32_bf16 v[8:11], v[136:139], v[222:225], v[8:11]
	v_mfma_f32_16x16x32_bf16 v[60:63], v[132:135], v[192:195], v[60:63]
	v_mfma_f32_16x16x32_bf16 v[56:59], v[140:143], v[192:195], v[56:59]
	v_mfma_f32_16x16x32_bf16 v[44:47], v[132:135], v[210:213], v[44:47]
	v_mfma_f32_16x16x32_bf16 v[40:43], v[140:143], v[210:213], v[40:43]
	v_mfma_f32_16x16x32_bf16 v[28:31], v[132:135], v[218:221], v[28:31]
	v_mfma_f32_16x16x32_bf16 v[24:27], v[140:143], v[218:221], v[24:27]
	v_mfma_f32_16x16x32_bf16 v[12:15], v[132:135], v[226:229], v[12:15]
	v_mfma_f32_16x16x32_bf16 v[8:11], v[140:143], v[226:229], v[8:11]
	s_setprio 0
	s_setprio 1
	v_mfma_f32_16x16x32_bf16 v[52:55], v[144:147], v[188:191], v[52:55]
	v_mfma_f32_16x16x32_bf16 v[48:51], v[152:155], v[188:191], v[48:51]
	v_mfma_f32_16x16x32_bf16 v[36:39], v[144:147], v[206:209], v[36:39]
	v_mfma_f32_16x16x32_bf16 v[32:35], v[152:155], v[206:209], v[32:35]
	v_mfma_f32_16x16x32_bf16 v[20:23], v[144:147], v[214:217], v[20:23]
	v_mfma_f32_16x16x32_bf16 v[16:19], v[152:155], v[214:217], v[16:19]
	v_mfma_f32_16x16x32_bf16 v[4:7], v[144:147], v[222:225], v[4:7]
	v_mfma_f32_16x16x32_bf16 v[0:3], v[152:155], v[222:225], v[0:3]
	v_mfma_f32_16x16x32_bf16 v[52:55], v[148:151], v[192:195], v[52:55]
	v_mfma_f32_16x16x32_bf16 v[48:51], v[156:159], v[192:195], v[48:51]
	v_mfma_f32_16x16x32_bf16 v[36:39], v[148:151], v[210:213], v[36:39]
	v_mfma_f32_16x16x32_bf16 v[32:35], v[156:159], v[210:213], v[32:35]
	v_mfma_f32_16x16x32_bf16 v[20:23], v[148:151], v[218:221], v[20:23]
	v_mfma_f32_16x16x32_bf16 v[16:19], v[156:159], v[218:221], v[16:19]
	v_mfma_f32_16x16x32_bf16 v[4:7], v[148:151], v[226:229], v[4:7]
	v_mfma_f32_16x16x32_bf16 v[0:3], v[156:159], v[226:229], v[0:3]
	s_setprio 0
	s_barrier
	s_add_i32 s53, 0, 0x18000
	s_add_i32 s54, 0, 0x1c000
	v_add_u32_e32 v140, s53, v199
	v_add_u32_e32 v156, s54, v199
	ds_read_b128 v[128:131], v140
	ds_read_b128 v[132:135], v140 offset:1024
	ds_read_b128 v[136:139], v140 offset:2048
	ds_read_b128 v[140:143], v140 offset:3072
	ds_read_b128 v[144:147], v156
	ds_read_b128 v[148:151], v156 offset:1024
	ds_read_b128 v[152:155], v156 offset:2048
	ds_read_b128 v[156:159], v156 offset:3072
	s_add_u32 s30, s30, 0x40000
	s_addc_u32 s31, s31, 0
	s_mov_b32 m0, s40
	v_lshl_add_u64 v[236:237], s[30:31], 0, v[160:161]
	ds_read_b128 v[188:191], v203 offset:32768
	ds_read_b128 v[192:195], v203 offset:33792
	ds_read_b128 v[206:209], v203 offset:34816
	ds_read_b128 v[210:213], v203 offset:35840
	ds_read_b128 v[214:217], v203 offset:36864
	ds_read_b128 v[218:221], v203 offset:37888
	ds_read_b128 v[222:225], v203 offset:38912
	ds_read_b128 v[226:229], v203 offset:39936
	global_load_lds_dwordx4 v[236:237], off
	v_lshl_add_u64 v[236:237], s[30:31], 0, v[164:165]
	s_mov_b32 m0, s41
	s_nop 0
	global_load_lds_dwordx4 v[236:237], off
	s_waitcnt vmcnt(8)
	s_waitcnt lgkmcnt(0)
	s_barrier
	s_setprio 1
	v_mfma_f32_16x16x32_bf16 v[124:127], v[128:131], v[188:191], v[124:127]
	v_mfma_f32_16x16x32_bf16 v[120:123], v[136:139], v[188:191], v[120:123]
	v_mfma_f32_16x16x32_bf16 v[108:111], v[128:131], v[206:209], v[108:111]
	v_mfma_f32_16x16x32_bf16 v[104:107], v[136:139], v[206:209], v[104:107]
	v_mfma_f32_16x16x32_bf16 v[92:95], v[128:131], v[214:217], v[92:95]
	v_mfma_f32_16x16x32_bf16 v[88:91], v[136:139], v[214:217], v[88:91]
	v_mfma_f32_16x16x32_bf16 v[76:79], v[128:131], v[222:225], v[76:79]
	v_mfma_f32_16x16x32_bf16 v[72:75], v[136:139], v[222:225], v[72:75]
	v_mfma_f32_16x16x32_bf16 v[124:127], v[132:135], v[192:195], v[124:127]
	v_mfma_f32_16x16x32_bf16 v[120:123], v[140:143], v[192:195], v[120:123]
	v_mfma_f32_16x16x32_bf16 v[108:111], v[132:135], v[210:213], v[108:111]
	v_mfma_f32_16x16x32_bf16 v[104:107], v[140:143], v[210:213], v[104:107]
	v_mfma_f32_16x16x32_bf16 v[92:95], v[132:135], v[218:221], v[92:95]
	v_mfma_f32_16x16x32_bf16 v[88:91], v[140:143], v[218:221], v[88:91]
	v_mfma_f32_16x16x32_bf16 v[76:79], v[132:135], v[226:229], v[76:79]
	v_mfma_f32_16x16x32_bf16 v[72:75], v[140:143], v[226:229], v[72:75]
	s_setprio 0
	s_setprio 1
	v_mfma_f32_16x16x32_bf16 v[116:119], v[144:147], v[188:191], v[116:119]
	v_mfma_f32_16x16x32_bf16 v[112:115], v[152:155], v[188:191], v[112:115]
	v_mfma_f32_16x16x32_bf16 v[100:103], v[144:147], v[206:209], v[100:103]
	v_mfma_f32_16x16x32_bf16 v[96:99], v[152:155], v[206:209], v[96:99]
	v_mfma_f32_16x16x32_bf16 v[84:87], v[144:147], v[214:217], v[84:87]
	v_mfma_f32_16x16x32_bf16 v[80:83], v[152:155], v[214:217], v[80:83]
	v_mfma_f32_16x16x32_bf16 v[68:71], v[144:147], v[222:225], v[68:71]
	v_mfma_f32_16x16x32_bf16 v[64:67], v[152:155], v[222:225], v[64:67]
	v_mfma_f32_16x16x32_bf16 v[116:119], v[148:151], v[192:195], v[116:119]
	v_mfma_f32_16x16x32_bf16 v[112:115], v[156:159], v[192:195], v[112:115]
	v_mfma_f32_16x16x32_bf16 v[100:103], v[148:151], v[210:213], v[100:103]
	v_mfma_f32_16x16x32_bf16 v[96:99], v[156:159], v[210:213], v[96:99]
	v_mfma_f32_16x16x32_bf16 v[84:87], v[148:151], v[218:221], v[84:87]
	v_mfma_f32_16x16x32_bf16 v[80:83], v[156:159], v[218:221], v[80:83]
	v_mfma_f32_16x16x32_bf16 v[68:71], v[148:151], v[226:229], v[68:71]
	v_mfma_f32_16x16x32_bf16 v[64:67], v[156:159], v[226:229], v[64:67]
	s_setprio 0
	s_barrier
; #define PG8_STAGE(bufoff, gbase, voff) do { _Pragma("unroll") for (int _i = 0; _i < 2; ++_i) \
;         __builtin_amdgcn_global_load_lds((const unsigned*)((const char*)(gbase) + (voff)[_i]), (PG8_LAS unsigned*)(lds + (bufoff) + ldsw + _i * 8192), 16, 0, 0); } while (0)
; #define PG8_LDA(dst, b, h) do { _Pragma("unroll") for (int m = 0; m < 4; ++m) _Pragma("unroll") for (int k = 0; k < 2; ++k) dst[m][k] = *(const PG8_LAS bf16x8*)(lds + PG8_SA(b, h) + aoff + m * 2048 + k * 1024); } while (0)
; #define PG8_MMA(ai, bj, At, Bt) do { __builtin_amdgcn_s_setprio(1); _Pragma("unroll") for (int m = 0; m < 4; ++m) _Pragma("unroll") for (int n = 0; n < 2; ++n) _Pragma("unroll") for (int k = 0; k < 2; ++k) \
;         acc[ai][bj][m][n] = __builtin_amdgcn_mfma_f32_16x16x32_bf16(Bt[n][k], At[m][k], acc[ai][bj][m][n], 0, 0, 0); __builtin_amdgcn_s_setprio(0); } while (0)
; #define PG8_WAIT_V(n) asm volatile("s_waitcnt vmcnt(" #n ")" ::: "memory")
; #define PG8_WAIT_L(n) asm volatile("s_waitcnt lgkmcnt(" #n ")" ::: "memory")
; #define PG8_BAR __builtin_amdgcn_s_barrier()
; #define PG8_SCHED __builtin_amdgcn_sched_barrier(0)
; template <class Epi, class Sched, bool ALIGN_EPI = false, bool SP2 = false>
; __device__ __forceinline__ void gemm_phase(PG8_LAS unsigned char* lds, const Gemm g, const Sched& S, const Epi& E) {
;     ...
;             PG8_LDA(At, 1, 1); PG8_STAGE(PG8_SB(1, 0), b3, voffB); PG8_STAGE(PG8_SB(1, 1), b3 + hstepB, voffB); PG8_STAGE(PG8_SA(1, 0), a3, voffA);
;             PG8_WAIT_V(8); PG8_WAIT_L(0); PG8_BAR; PG8_MMA(1, 0, At, B0); PG8_MMA(1, 1, At, B1); PG8_BAR; PG8_SCHED;
;     ...
;         if constexpr (ALIGN_EPI) { if (wr == 0) PG8_BAR; }
	s_add_i32 s30, s53, s38
	v_lshl_add_u64 v[196:197], v[196:197], 0, s[14:15]
	s_mov_b32 m0, s30
	ds_read_b128 v[188:191], v203 offset:49152
	ds_read_b128 v[192:195], v203 offset:50176
	ds_read_b128 v[206:209], v203 offset:51200
	ds_read_b128 v[210:213], v203 offset:52224
	ds_read_b128 v[214:217], v203 offset:53248
	ds_read_b128 v[218:221], v203 offset:54272
	ds_read_b128 v[222:225], v203 offset:55296
	ds_read_b128 v[226:229], v203 offset:56320
	global_load_lds_dwordx4 v[196:197], off
	s_add_i32 m0, s30, 0x2000
	s_add_u32 s28, s28, 0x10080
	v_lshl_add_u64 v[196:197], v[230:231], 0, s[14:15]
	s_addc_u32 s29, s29, 0
	s_add_i32 s30, s54, s38
	global_load_lds_dwordx4 v[196:197], off
	v_lshl_add_u64 v[196:197], s[28:29], 0, v[162:163]
	s_mov_b32 m0, s30
	s_nop 0
	global_load_lds_dwordx4 v[196:197], off
	v_lshl_add_u64 v[196:197], s[28:29], 0, v[166:167]
	s_add_i32 m0, s30, 0x2000
	s_nop 0
	global_load_lds_dwordx4 v[196:197], off
	v_lshl_add_u64 v[196:197], v[232:233], 0, s[14:15]
	s_mov_b32 m0, s43
	s_nop 0
	global_load_lds_dwordx4 v[196:197], off
	v_lshl_add_u64 v[196:197], v[234:235], 0, s[14:15]
	s_mov_b32 m0, s44
	s_nop 0
	global_load_lds_dwordx4 v[196:197], off
	s_waitcnt vmcnt(8)
	s_waitcnt lgkmcnt(0)
	s_barrier
	s_setprio 1
	v_mfma_f32_16x16x32_bf16 v[60:63], v[128:131], v[188:191], v[60:63]
	v_mfma_f32_16x16x32_bf16 v[56:59], v[136:139], v[188:191], v[56:59]
	v_mfma_f32_16x16x32_bf16 v[44:47], v[128:131], v[206:209], v[44:47]
	v_mfma_f32_16x16x32_bf16 v[40:43], v[136:139], v[206:209], v[40:43]
	v_mfma_f32_16x16x32_bf16 v[28:31], v[128:131], v[214:217], v[28:31]
	v_mfma_f32_16x16x32_bf16 v[24:27], v[136:139], v[214:217], v[24:27]
	v_mfma_f32_16x16x32_bf16 v[12:15], v[128:131], v[222:225], v[12:15]
	v_mfma_f32_16x16x32_bf16 v[8:11], v[136:139], v[222:225], v[8:11]
	v_mfma_f32_16x16x32_bf16 v[60:63], v[132:135], v[192:195], v[60:63]
	v_mfma_f32_16x16x32_bf16 v[56:59], v[140:143], v[192:195], v[56:59]
	v_mfma_f32_16x16x32_bf16 v[44:47], v[132:135], v[210:213], v[44:47]
	v_mfma_f32_16x16x32_bf16 v[40:43], v[140:143], v[210:213], v[40:43]
	v_mfma_f32_16x16x32_bf16 v[28:31], v[132:135], v[218:221], v[28:31]
	v_mfma_f32_16x16x32_bf16 v[24:27], v[140:143], v[218:221], v[24:27]
	v_mfma_f32_16x16x32_bf16 v[12:15], v[132:135], v[226:229], v[12:15]
	v_mfma_f32_16x16x32_bf16 v[8:11], v[140:143], v[226:229], v[8:11]
	s_setprio 0
	s_setprio 1
	v_mfma_f32_16x16x32_bf16 v[52:55], v[144:147], v[188:191], v[52:55]
	v_mfma_f32_16x16x32_bf16 v[48:51], v[152:155], v[188:191], v[48:51]
	v_mfma_f32_16x16x32_bf16 v[36:39], v[144:147], v[206:209], v[36:39]
	v_mfma_f32_16x16x32_bf16 v[32:35], v[152:155], v[206:209], v[32:35]
	v_mfma_f32_16x16x32_bf16 v[20:23], v[144:147], v[214:217], v[20:23]
	v_mfma_f32_16x16x32_bf16 v[16:19], v[152:155], v[214:217], v[16:19]
	v_mfma_f32_16x16x32_bf16 v[4:7], v[144:147], v[222:225], v[4:7]
	v_mfma_f32_16x16x32_bf16 v[0:3], v[152:155], v[222:225], v[0:3]
	v_mfma_f32_16x16x32_bf16 v[52:55], v[148:151], v[192:195], v[52:55]
	v_mfma_f32_16x16x32_bf16 v[48:51], v[156:159], v[192:195], v[48:51]
	v_mfma_f32_16x16x32_bf16 v[36:39], v[148:151], v[210:213], v[36:39]
	v_mfma_f32_16x16x32_bf16 v[32:35], v[156:159], v[210:213], v[32:35]
	v_mfma_f32_16x16x32_bf16 v[20:23], v[148:151], v[218:221], v[20:23]
	v_mfma_f32_16x16x32_bf16 v[16:19], v[156:159], v[218:221], v[16:19]
	v_mfma_f32_16x16x32_bf16 v[4:7], v[148:151], v[226:229], v[4:7]
	v_mfma_f32_16x16x32_bf16 v[0:3], v[156:159], v[226:229], v[0:3]
	s_setprio 0
	s_barrier
	s_add_i32 s52, s52, 2
	s_add_u32 s0, s0, 0x100
	s_addc_u32 s1, s1, 0
	s_add_u32 s50, s50, 0x100
	s_addc_u32 s51, s51, 0
	s_cmp_gt_u32 s52, 13
	s_cbranch_scc0 .LBB0_479
	s_and_b64 vcc, exec, s[16:17]
	s_cbranch_vccz .LBB0_482
	s_barrier

; #define PG8_STAGE(bufoff, gbase, voff) do { _Pragma("unroll") for (int _i = 0; _i < 2; ++_i) \
;         __builtin_amdgcn_global_load_lds((const unsigned*)((const char*)(gbase) + (voff)[_i]), (PG8_LAS unsigned*)(lds + (bufoff) + ldsw + _i * 8192), 16, 0, 0); } while (0)
; #define PG8_LDA(dst, b, h) do { _Pragma("unroll") for (int m = 0; m < 4; ++m) _Pragma("unroll") for (int k = 0; k < 2; ++k) dst[m][k] = *(const PG8_LAS bf16x8*)(lds + PG8_SA(b, h) + aoff + m * 2048 + k * 1024); } while (0)
; #define PG8_LDB(dst, b, h) do { _Pragma("unroll") for (int n = 0; n < 2; ++n) _Pragma("unroll") for (int k = 0; k < 2; ++k) dst[n][k] = *(const PG8_LAS bf16x8*)(lds + PG8_SB(b, h) + boff + n * 2048 + k * 1024); } while (0)
; #define PG8_MMA(ai, bj, At, Bt) do { __builtin_amdgcn_s_setprio(1); _Pragma("unroll") for (int m = 0; m < 4; ++m) _Pragma("unroll") for (int n = 0; n < 2; ++n) _Pragma("unroll") for (int k = 0; k < 2; ++k) \
;         acc[ai][bj][m][n] = __builtin_amdgcn_mfma_f32_16x16x32_bf16(Bt[n][k], At[m][k], acc[ai][bj][m][n], 0, 0, 0); __builtin_amdgcn_s_setprio(0); } while (0)
; #define PG8_WAIT_V(n) asm volatile("s_waitcnt vmcnt(" #n ")" ::: "memory")
; #define PG8_WAIT_L(n) asm volatile("s_waitcnt lgkmcnt(" #n ")" ::: "memory")
; #define PG8_BAR __builtin_amdgcn_s_barrier()
; #define PG8_SCHED __builtin_amdgcn_sched_barrier(0)
; template <class Epi, class Sched, bool ALIGN_EPI = false, bool SP2 = false>
; __device__ __forceinline__ void gemm_phase(PG8_LAS unsigned char* lds, const Gemm g, const Sched& S, const Epi& E) {
;     ...
;             const char* a2 = last ? nA : cA + (size_t)(t + 2) * kstep; const char* b2 = last ? nB : cB + (size_t)(t + 2) * kstep;
;             const char* a3 = a2 + kstep; const char* b3 = b2 + kstep;
;             if (last && has_next) S.a_ready(nxt);
;             if constexpr (SP2) {
;             PG8_LDB(B0, 0, 0); PG8_LDB(B1, 0, 1); PG8_SCHED; PG8_LDA(At, 0, 0); PG8_STAGE(PG8_SA(1, 1), a1 + hstep, voffA);
;             PG8_WAIT_V(8); PG8_WAIT_L(0); PG8_BAR; PG8_MMA(0, 0, At, B0); PG8_MMA(0, 1, At, B1); PG8_BAR; PG8_SCHED;
;             PG8_LDA(At, 0, 1); PG8_STAGE(PG8_SB(0, 0), b2, voffB); PG8_STAGE(PG8_SB(0, 1), b2 + hstepB, voffB); PG8_STAGE(PG8_SA(0, 0), a2, voffA);
.LBB0_560:
	ds_read_b128 v[128:131], v219
	ds_read_b128 v[132:135], v219 offset:1024
	ds_read_b128 v[136:139], v219 offset:2048
	ds_read_b128 v[140:143], v219 offset:3072
	ds_read_b128 v[144:147], v220
	ds_read_b128 v[148:151], v220 offset:1024
	ds_read_b128 v[152:155], v220 offset:2048
	ds_read_b128 v[156:159], v220 offset:3072
	s_add_u32 s28, s26, 0xfffc0080
	s_addc_u32 s29, s27, -1
	s_cmp_eq_u32 s54, 12
	s_cselect_b32 s31, s19, s29
	s_cselect_b32 s30, s25, s28
	s_cselect_b32 s29, s17, s53
	s_cselect_b32 s28, s51, s52
	v_lshl_add_u64 v[230:231], s[26:27], 0, v[192:193]
	s_add_i32 m0, s38, 0xc000
	ds_read_b128 v[160:163], v221
	ds_read_b128 v[164:167], v221 offset:1024
	ds_read_b128 v[168:171], v221 offset:2048
	ds_read_b128 v[172:175], v221 offset:3072
	ds_read_b128 v[204:207], v221 offset:4096
	ds_read_b128 v[208:211], v221 offset:5120
	ds_read_b128 v[212:215], v221 offset:6144
	ds_read_b128 v[226:229], v221 offset:7168
	global_load_lds_dwordx4 v[230:231], off
	v_lshl_add_u64 v[230:231], s[26:27], 0, v[194:195]
	s_add_i32 m0, s38, 0xe000
	s_nop 0
	global_load_lds_dwordx4 v[230:231], off
	s_waitcnt vmcnt(8)
	s_waitcnt lgkmcnt(0)
	s_barrier
	s_setprio 1
	v_mfma_f32_16x16x32_bf16 v[124:127], v[128:131], v[160:163], v[124:127]
	v_mfma_f32_16x16x32_bf16 v[120:123], v[136:139], v[160:163], v[120:123]
	v_mfma_f32_16x16x32_bf16 v[108:111], v[128:131], v[168:171], v[108:111]
	v_mfma_f32_16x16x32_bf16 v[104:107], v[136:139], v[168:171], v[104:107]
	v_mfma_f32_16x16x32_bf16 v[92:95], v[128:131], v[204:207], v[92:95]
	v_mfma_f32_16x16x32_bf16 v[88:91], v[136:139], v[204:207], v[88:91]
	v_mfma_f32_16x16x32_bf16 v[76:79], v[128:131], v[212:215], v[76:79]
	v_mfma_f32_16x16x32_bf16 v[72:75], v[136:139], v[212:215], v[72:75]
	v_mfma_f32_16x16x32_bf16 v[124:127], v[132:135], v[164:167], v[124:127]
	v_mfma_f32_16x16x32_bf16 v[120:123], v[140:143], v[164:167], v[120:123]
	v_mfma_f32_16x16x32_bf16 v[108:111], v[132:135], v[172:175], v[108:111]
	v_mfma_f32_16x16x32_bf16 v[104:107], v[140:143], v[172:175], v[104:107]
	v_mfma_f32_16x16x32_bf16 v[92:95], v[132:135], v[208:211], v[92:95]
	v_mfma_f32_16x16x32_bf16 v[88:91], v[140:143], v[208:211], v[88:91]
	v_mfma_f32_16x16x32_bf16 v[76:79], v[132:135], v[226:229], v[76:79]
	v_mfma_f32_16x16x32_bf16 v[72:75], v[140:143], v[226:229], v[72:75]
	s_setprio 0
	s_setprio 1
	v_mfma_f32_16x16x32_bf16 v[116:119], v[144:147], v[160:163], v[116:119]
	v_mfma_f32_16x16x32_bf16 v[112:115], v[152:155], v[160:163], v[112:115]
	v_mfma_f32_16x16x32_bf16 v[100:103], v[144:147], v[168:171], v[100:103]
	v_mfma_f32_16x16x32_bf16 v[96:99], v[152:155], v[168:171], v[96:99]
	v_mfma_f32_16x16x32_bf16 v[84:87], v[144:147], v[204:207], v[84:87]
	v_mfma_f32_16x16x32_bf16 v[80:83], v[152:155], v[204:207], v[80:83]
	v_mfma_f32_16x16x32_bf16 v[68:71], v[144:147], v[212:215], v[68:71]
	v_mfma_f32_16x16x32_bf16 v[64:67], v[152:155], v[212:215], v[64:67]
	v_mfma_f32_16x16x32_bf16 v[116:119], v[148:151], v[164:167], v[116:119]
	v_mfma_f32_16x16x32_bf16 v[112:115], v[156:159], v[164:167], v[112:115]
	v_mfma_f32_16x16x32_bf16 v[100:103], v[148:151], v[172:175], v[100:103]
	v_mfma_f32_16x16x32_bf16 v[96:99], v[156:159], v[172:175], v[96:99]
	v_mfma_f32_16x16x32_bf16 v[84:87], v[148:151], v[208:211], v[84:87]
	v_mfma_f32_16x16x32_bf16 v[80:83], v[156:159], v[208:211], v[80:83]
	v_mfma_f32_16x16x32_bf16 v[68:71], v[148:151], v[226:229], v[68:71]
	v_mfma_f32_16x16x32_bf16 v[64:67], v[156:159], v[226:229], v[64:67]
	s_setprio 0
	s_barrier
	s_add_i32 s55, s48, s37
	v_lshl_add_u64 v[230:231], s[28:29], 0, v[180:181]
	s_mov_b32 m0, s55
	ds_read_b128 v[160:163], v221 offset:16384
	ds_read_b128 v[164:167], v221 offset:17408
	ds_read_b128 v[168:171], v221 offset:18432
	ds_read_b128 v[172:175], v221 offset:19456
	ds_read_b128 v[204:207], v221 offset:20480
	ds_read_b128 v[208:211], v221 offset:21504
	ds_read_b128 v[212:215], v221 offset:22528
	ds_read_b128 v[226:229], v221 offset:23552
	global_load_lds_dwordx4 v[230:231], off
	s_add_i32 m0, s55, 0x2000
	s_add_u32 s56, s28, 0x10000
	v_lshl_add_u64 v[232:233], s[28:29], 0, v[184:185]
	s_addc_u32 s57, s29, 0
	s_add_i32 s55, s49, s37
	global_load_lds_dwordx4 v[232:233], off
	v_lshl_add_u64 v[234:235], s[56:57], 0, v[180:181]
	s_mov_b32 m0, s55
	v_lshl_add_u64 v[236:237], s[30:31], 0, v[182:183]
	global_load_lds_dwordx4 v[234:235], off
	v_lshl_add_u64 v[234:235], s[56:57], 0, v[184:185]
	s_add_i32 m0, s55, 0x2000
	s_nop 0
	global_load_lds_dwordx4 v[234:235], off
	v_lshl_add_u64 v[234:235], s[30:31], 0, v[178:179]
	s_mov_b32 m0, s38
	s_nop 0
	global_load_lds_dwordx4 v[234:235], off
	s_mov_b32 m0, s39
	s_nop 0
	global_load_lds_dwordx4 v[236:237], off
	s_waitcnt vmcnt(8)
	s_waitcnt lgkmcnt(0)
	s_barrier
; #define PG8_STAGE(bufoff, gbase, voff) do { _Pragma("unroll") for (int _i = 0; _i < 2; ++_i) \
;         __builtin_amdgcn_global_load_lds((const unsigned*)((const char*)(gbase) + (voff)[_i]), (PG8_LAS unsigned*)(lds + (bufoff) + ldsw + _i * 8192), 16, 0, 0); } while (0)
; #define PG8_LDA(dst, b, h) do { _Pragma("unroll") for (int m = 0; m < 4; ++m) _Pragma("unroll") for (int k = 0; k < 2; ++k) dst[m][k] = *(const PG8_LAS bf16x8*)(lds + PG8_SA(b, h) + aoff + m * 2048 + k * 1024); } while (0)
; #define PG8_LDB(dst, b, h) do { _Pragma("unroll") for (int n = 0; n < 2; ++n) _Pragma("unroll") for (int k = 0; k < 2; ++k) dst[n][k] = *(const PG8_LAS bf16x8*)(lds + PG8_SB(b, h) + boff + n * 2048 + k * 1024); } while (0)
; #define PG8_MMA(ai, bj, At, Bt) do { __builtin_amdgcn_s_setprio(1); _Pragma("unroll") for (int m = 0; m < 4; ++m) _Pragma("unroll") for (int n = 0; n < 2; ++n) _Pragma("unroll") for (int k = 0; k < 2; ++k) \
;         acc[ai][bj][m][n] = __builtin_amdgcn_mfma_f32_16x16x32_bf16(Bt[n][k], At[m][k], acc[ai][bj][m][n], 0, 0, 0); __builtin_amdgcn_s_setprio(0); } while (0)
; #define PG8_WAIT_V(n) asm volatile("s_waitcnt vmcnt(" #n ")" ::: "memory")
; #define PG8_WAIT_L(n) asm volatile("s_waitcnt lgkmcnt(" #n ")" ::: "memory")
; #define PG8_BAR __builtin_amdgcn_s_barrier()
; #define PG8_SCHED __builtin_amdgcn_sched_barrier(0)
; template <class Epi, class Sched, bool ALIGN_EPI = false, bool SP2 = false>
; __device__ __forceinline__ void gemm_phase(PG8_LAS unsigned char* lds, const Gemm g, const Sched& S, const Epi& E) {
;     ...
;             PG8_WAIT_V(8); PG8_WAIT_L(0); PG8_BAR; PG8_MMA(1, 0, At, B0); PG8_MMA(1, 1, At, B1); PG8_BAR; PG8_SCHED;
;             PG8_LDB(B0, 1, 0); PG8_LDB(B1, 1, 1); PG8_SCHED; PG8_LDA(At, 1, 0); PG8_STAGE(PG8_SA(0, 1), a2 + hstep, voffA);
;             PG8_WAIT_V(8); PG8_WAIT_L(0); PG8_BAR; PG8_MMA(0, 0, At, B0); PG8_MMA(0, 1, At, B1); PG8_BAR; PG8_SCHED;
	s_setprio 1
	v_mfma_f32_16x16x32_bf16 v[60:63], v[128:131], v[160:163], v[60:63]
	v_mfma_f32_16x16x32_bf16 v[56:59], v[136:139], v[160:163], v[56:59]
	v_mfma_f32_16x16x32_bf16 v[44:47], v[128:131], v[168:171], v[44:47]
	v_mfma_f32_16x16x32_bf16 v[40:43], v[136:139], v[168:171], v[40:43]
	v_mfma_f32_16x16x32_bf16 v[28:31], v[128:131], v[204:207], v[28:31]
	v_mfma_f32_16x16x32_bf16 v[24:27], v[136:139], v[204:207], v[24:27]
	v_mfma_f32_16x16x32_bf16 v[12:15], v[128:131], v[212:215], v[12:15]
	v_mfma_f32_16x16x32_bf16 v[8:11], v[136:139], v[212:215], v[8:11]
	v_mfma_f32_16x16x32_bf16 v[60:63], v[132:135], v[164:167], v[60:63]
	v_mfma_f32_16x16x32_bf16 v[56:59], v[140:143], v[164:167], v[56:59]
	v_mfma_f32_16x16x32_bf16 v[44:47], v[132:135], v[172:175], v[44:47]
	v_mfma_f32_16x16x32_bf16 v[40:43], v[140:143], v[172:175], v[40:43]
	v_mfma_f32_16x16x32_bf16 v[28:31], v[132:135], v[208:211], v[28:31]
	v_mfma_f32_16x16x32_bf16 v[24:27], v[140:143], v[208:211], v[24:27]
	v_mfma_f32_16x16x32_bf16 v[12:15], v[132:135], v[226:229], v[12:15]
	v_mfma_f32_16x16x32_bf16 v[8:11], v[140:143], v[226:229], v[8:11]
	s_setprio 0
	s_setprio 1
	v_mfma_f32_16x16x32_bf16 v[52:55], v[144:147], v[160:163], v[52:55]
	v_mfma_f32_16x16x32_bf16 v[48:51], v[152:155], v[160:163], v[48:51]
	v_mfma_f32_16x16x32_bf16 v[36:39], v[144:147], v[168:171], v[36:39]
	v_mfma_f32_16x16x32_bf16 v[32:35], v[152:155], v[168:171], v[32:35]
	v_mfma_f32_16x16x32_bf16 v[20:23], v[144:147], v[204:207], v[20:23]
	v_mfma_f32_16x16x32_bf16 v[16:19], v[152:155], v[204:207], v[16:19]
	v_mfma_f32_16x16x32_bf16 v[4:7], v[144:147], v[212:215], v[4:7]
	v_mfma_f32_16x16x32_bf16 v[0:3], v[152:155], v[212:215], v[0:3]
	v_mfma_f32_16x16x32_bf16 v[52:55], v[148:151], v[164:167], v[52:55]
	v_mfma_f32_16x16x32_bf16 v[48:51], v[156:159], v[164:167], v[48:51]
	v_mfma_f32_16x16x32_bf16 v[36:39], v[148:151], v[172:175], v[36:39]
	v_mfma_f32_16x16x32_bf16 v[32:35], v[156:159], v[172:175], v[32:35]
	v_mfma_f32_16x16x32_bf16 v[20:23], v[148:151], v[208:211], v[20:23]
	v_mfma_f32_16x16x32_bf16 v[16:19], v[156:159], v[208:211], v[16:19]
	v_mfma_f32_16x16x32_bf16 v[4:7], v[148:151], v[226:229], v[4:7]
	v_mfma_f32_16x16x32_bf16 v[0:3], v[156:159], v[226:229], v[0:3]
	s_setprio 0
	s_barrier
	s_add_i32 s55, 0, 0x18000
	s_add_i32 s56, 0, 0x1c000
	v_add_u32_e32 v140, s55, v217
	v_add_u32_e32 v156, s56, v217
	ds_read_b128 v[128:131], v140
	ds_read_b128 v[132:135], v140 offset:1024
	ds_read_b128 v[136:139], v140 offset:2048
	ds_read_b128 v[140:143], v140 offset:3072
	ds_read_b128 v[144:147], v156
	ds_read_b128 v[148:151], v156 offset:1024
	ds_read_b128 v[152:155], v156 offset:2048
	ds_read_b128 v[156:159], v156 offset:3072
	s_add_u32 s30, s30, 0x40000
	s_addc_u32 s31, s31, 0
	s_mov_b32 m0, s40
	v_lshl_add_u64 v[238:239], s[30:31], 0, v[178:179]
	ds_read_b128 v[160:163], v221 offset:32768
	ds_read_b128 v[164:167], v221 offset:33792
	ds_read_b128 v[168:171], v221 offset:34816
	ds_read_b128 v[172:175], v221 offset:35840
	ds_read_b128 v[204:207], v221 offset:36864
	ds_read_b128 v[208:211], v221 offset:37888
	ds_read_b128 v[212:215], v221 offset:38912
	ds_read_b128 v[226:229], v221 offset:39936
	global_load_lds_dwordx4 v[238:239], off
	v_lshl_add_u64 v[238:239], s[30:31], 0, v[182:183]
	s_mov_b32 m0, s41
	s_nop 0
	global_load_lds_dwordx4 v[238:239], off
	s_waitcnt vmcnt(8)
	s_waitcnt lgkmcnt(0)
	s_barrier
	s_setprio 1
	v_mfma_f32_16x16x32_bf16 v[124:127], v[128:131], v[160:163], v[124:127]
	v_mfma_f32_16x16x32_bf16 v[120:123], v[136:139], v[160:163], v[120:123]
	v_mfma_f32_16x16x32_bf16 v[108:111], v[128:131], v[168:171], v[108:111]
	v_mfma_f32_16x16x32_bf16 v[104:107], v[136:139], v[168:171], v[104:107]
	v_mfma_f32_16x16x32_bf16 v[92:95], v[128:131], v[204:207], v[92:95]
	v_mfma_f32_16x16x32_bf16 v[88:91], v[136:139], v[204:207], v[88:91]
	v_mfma_f32_16x16x32_bf16 v[76:79], v[128:131], v[212:215], v[76:79]
	v_mfma_f32_16x16x32_bf16 v[72:75], v[136:139], v[212:215], v[72:75]
	v_mfma_f32_16x16x32_bf16 v[124:127], v[132:135], v[164:167], v[124:127]
	v_mfma_f32_16x16x32_bf16 v[120:123], v[140:143], v[164:167], v[120:123]
	v_mfma_f32_16x16x32_bf16 v[108:111], v[132:135], v[172:175], v[108:111]
	v_mfma_f32_16x16x32_bf16 v[104:107], v[140:143], v[172:175], v[104:107]
	v_mfma_f32_16x16x32_bf16 v[92:95], v[132:135], v[208:211], v[92:95]
	v_mfma_f32_16x16x32_bf16 v[88:91], v[140:143], v[208:211], v[88:91]
	v_mfma_f32_16x16x32_bf16 v[76:79], v[132:135], v[226:229], v[76:79]
	v_mfma_f32_16x16x32_bf16 v[72:75], v[140:143], v[226:229], v[72:75]
	s_setprio 0
	s_setprio 1
	v_mfma_f32_16x16x32_bf16 v[116:119], v[144:147], v[160:163], v[116:119]
	v_mfma_f32_16x16x32_bf16 v[112:115], v[152:155], v[160:163], v[112:115]
	v_mfma_f32_16x16x32_bf16 v[100:103], v[144:147], v[168:171], v[100:103]
	v_mfma_f32_16x16x32_bf16 v[96:99], v[152:155], v[168:171], v[96:99]
	v_mfma_f32_16x16x32_bf16 v[84:87], v[144:147], v[204:207], v[84:87]
	v_mfma_f32_16x16x32_bf16 v[80:83], v[152:155], v[204:207], v[80:83]
	v_mfma_f32_16x16x32_bf16 v[68:71], v[144:147], v[212:215], v[68:71]
	v_mfma_f32_16x16x32_bf16 v[64:67], v[152:155], v[212:215], v[64:67]
	v_mfma_f32_16x16x32_bf16 v[116:119], v[148:151], v[164:167], v[116:119]
	v_mfma_f32_16x16x32_bf16 v[112:115], v[156:159], v[164:167], v[112:115]
	v_mfma_f32_16x16x32_bf16 v[100:103], v[148:151], v[172:175], v[100:103]
	v_mfma_f32_16x16x32_bf16 v[96:99], v[156:159], v[172:175], v[96:99]
	v_mfma_f32_16x16x32_bf16 v[84:87], v[148:151], v[208:211], v[84:87]
	v_mfma_f32_16x16x32_bf16 v[80:83], v[156:159], v[208:211], v[80:83]
	v_mfma_f32_16x16x32_bf16 v[68:71], v[148:151], v[226:229], v[68:71]
	v_mfma_f32_16x16x32_bf16 v[64:67], v[156:159], v[226:229], v[64:67]
	s_setprio 0
	s_barrier
; #define PG8_STAGE(bufoff, gbase, voff) do { _Pragma("unroll") for (int _i = 0; _i < 2; ++_i) \
;         __builtin_amdgcn_global_load_lds((const unsigned*)((const char*)(gbase) + (voff)[_i]), (PG8_LAS unsigned*)(lds + (bufoff) + ldsw + _i * 8192), 16, 0, 0); } while (0)
; #define PG8_LDA(dst, b, h) do { _Pragma("unroll") for (int m = 0; m < 4; ++m) _Pragma("unroll") for (int k = 0; k < 2; ++k) dst[m][k] = *(const PG8_LAS bf16x8*)(lds + PG8_SA(b, h) + aoff + m * 2048 + k * 1024); } while (0)
; #define PG8_MMA(ai, bj, At, Bt) do { __builtin_amdgcn_s_setprio(1); _Pragma("unroll") for (int m = 0; m < 4; ++m) _Pragma("unroll") for (int n = 0; n < 2; ++n) _Pragma("unroll") for (int k = 0; k < 2; ++k) \
;         acc[ai][bj][m][n] = __builtin_amdgcn_mfma_f32_16x16x32_bf16(Bt[n][k], At[m][k], acc[ai][bj][m][n], 0, 0, 0); __builtin_amdgcn_s_setprio(0); } while (0)
; #define PG8_WAIT_V(n) asm volatile("s_waitcnt vmcnt(" #n ")" ::: "memory")
; #define PG8_WAIT_L(n) asm volatile("s_waitcnt lgkmcnt(" #n ")" ::: "memory")
; #define PG8_BAR __builtin_amdgcn_s_barrier()
; #define PG8_SCHED __builtin_amdgcn_sched_barrier(0)
; template <class Epi, class Sched, bool ALIGN_EPI = false, bool SP2 = false>
; __device__ __forceinline__ void gemm_phase(PG8_LAS unsigned char* lds, const Gemm g, const Sched& S, const Epi& E) {
;     ...
;             PG8_LDA(At, 1, 1); PG8_STAGE(PG8_SB(1, 0), b3, voffB); PG8_STAGE(PG8_SB(1, 1), b3 + hstepB, voffB); PG8_STAGE(PG8_SA(1, 0), a3, voffA);
;             PG8_WAIT_V(8); PG8_WAIT_L(0); PG8_BAR; PG8_MMA(1, 0, At, B0); PG8_MMA(1, 1, At, B1); PG8_BAR; PG8_SCHED;
;     ...
;         if constexpr (ALIGN_EPI) { if (wr == 0) PG8_BAR; }
	s_add_i32 s30, s55, s37
	v_lshl_add_u64 v[230:231], v[230:231], 0, s[12:13]
	s_mov_b32 m0, s30
	ds_read_b128 v[160:163], v221 offset:49152
	ds_read_b128 v[164:167], v221 offset:50176
	ds_read_b128 v[168:171], v221 offset:51200
	ds_read_b128 v[172:175], v221 offset:52224
	ds_read_b128 v[204:207], v221 offset:53248
	ds_read_b128 v[208:211], v221 offset:54272
	ds_read_b128 v[212:215], v221 offset:55296
	ds_read_b128 v[226:229], v221 offset:56320
	global_load_lds_dwordx4 v[230:231], off
	s_add_i32 m0, s30, 0x2000
	s_add_u32 s28, s28, 0x10080
	v_lshl_add_u64 v[230:231], v[232:233], 0, s[12:13]
	s_addc_u32 s29, s29, 0
	s_add_i32 s30, s56, s37
	global_load_lds_dwordx4 v[230:231], off
	v_lshl_add_u64 v[230:231], s[28:29], 0, v[180:181]
	s_mov_b32 m0, s30
	s_nop 0
	global_load_lds_dwordx4 v[230:231], off
	v_lshl_add_u64 v[230:231], s[28:29], 0, v[184:185]
	s_add_i32 m0, s30, 0x2000
	s_nop 0
	global_load_lds_dwordx4 v[230:231], off
	v_lshl_add_u64 v[230:231], v[234:235], 0, s[12:13]
	s_mov_b32 m0, s43
	s_nop 0
	global_load_lds_dwordx4 v[230:231], off
	v_lshl_add_u64 v[230:231], v[236:237], 0, s[12:13]
	s_mov_b32 m0, s44
	s_nop 0
	global_load_lds_dwordx4 v[230:231], off
	s_waitcnt vmcnt(8)
	s_waitcnt lgkmcnt(0)
	s_barrier
	s_setprio 1
	v_mfma_f32_16x16x32_bf16 v[60:63], v[128:131], v[160:163], v[60:63]
	v_mfma_f32_16x16x32_bf16 v[56:59], v[136:139], v[160:163], v[56:59]
	v_mfma_f32_16x16x32_bf16 v[44:47], v[128:131], v[168:171], v[44:47]
	v_mfma_f32_16x16x32_bf16 v[40:43], v[136:139], v[168:171], v[40:43]
	v_mfma_f32_16x16x32_bf16 v[28:31], v[128:131], v[204:207], v[28:31]
	v_mfma_f32_16x16x32_bf16 v[24:27], v[136:139], v[204:207], v[24:27]
	v_mfma_f32_16x16x32_bf16 v[12:15], v[128:131], v[212:215], v[12:15]
	v_mfma_f32_16x16x32_bf16 v[8:11], v[136:139], v[212:215], v[8:11]
	v_mfma_f32_16x16x32_bf16 v[60:63], v[132:135], v[164:167], v[60:63]
	v_mfma_f32_16x16x32_bf16 v[56:59], v[140:143], v[164:167], v[56:59]
	v_mfma_f32_16x16x32_bf16 v[44:47], v[132:135], v[172:175], v[44:47]
	v_mfma_f32_16x16x32_bf16 v[40:43], v[140:143], v[172:175], v[40:43]
	v_mfma_f32_16x16x32_bf16 v[28:31], v[132:135], v[208:211], v[28:31]
	v_mfma_f32_16x16x32_bf16 v[24:27], v[140:143], v[208:211], v[24:27]
	v_mfma_f32_16x16x32_bf16 v[12:15], v[132:135], v[226:229], v[12:15]
	v_mfma_f32_16x16x32_bf16 v[8:11], v[140:143], v[226:229], v[8:11]
	s_setprio 0
	s_setprio 1
	v_mfma_f32_16x16x32_bf16 v[52:55], v[144:147], v[160:163], v[52:55]
	v_mfma_f32_16x16x32_bf16 v[48:51], v[152:155], v[160:163], v[48:51]
	v_mfma_f32_16x16x32_bf16 v[36:39], v[144:147], v[168:171], v[36:39]
	v_mfma_f32_16x16x32_bf16 v[32:35], v[152:155], v[168:171], v[32:35]
	v_mfma_f32_16x16x32_bf16 v[20:23], v[144:147], v[204:207], v[20:23]
	v_mfma_f32_16x16x32_bf16 v[16:19], v[152:155], v[204:207], v[16:19]
	v_mfma_f32_16x16x32_bf16 v[4:7], v[144:147], v[212:215], v[4:7]
	v_mfma_f32_16x16x32_bf16 v[0:3], v[152:155], v[212:215], v[0:3]
	v_mfma_f32_16x16x32_bf16 v[52:55], v[148:151], v[164:167], v[52:55]
	v_mfma_f32_16x16x32_bf16 v[48:51], v[156:159], v[164:167], v[48:51]
	v_mfma_f32_16x16x32_bf16 v[36:39], v[148:151], v[172:175], v[36:39]
	v_mfma_f32_16x16x32_bf16 v[32:35], v[156:159], v[172:175], v[32:35]
	v_mfma_f32_16x16x32_bf16 v[20:23], v[148:151], v[208:211], v[20:23]
	v_mfma_f32_16x16x32_bf16 v[16:19], v[156:159], v[208:211], v[16:19]
	v_mfma_f32_16x16x32_bf16 v[4:7], v[148:151], v[226:229], v[4:7]
	v_mfma_f32_16x16x32_bf16 v[0:3], v[156:159], v[226:229], v[0:3]
	s_setprio 0
	s_barrier
	s_add_i32 s54, s54, 2
	s_add_u32 s26, s26, 0x100
	s_addc_u32 s27, s27, 0
	s_add_u32 s52, s52, 0x100
	s_addc_u32 s53, s53, 0
	s_cmp_gt_u32 s54, 13
	s_cbranch_scc0 .LBB0_560
	s_and_b64 vcc, exec, s[14:15]
	s_cbranch_vccz .LBB0_563
	s_barrier

; #define PG8_STAGE(bufoff, gbase, voff) do { _Pragma("unroll") for (int _i = 0; _i < 2; ++_i) \
;         __builtin_amdgcn_global_load_lds((const unsigned*)((const char*)(gbase) + (voff)[_i]), (PG8_LAS unsigned*)(lds + (bufoff) + ldsw + _i * 8192), 16, 0, 0); } while (0)
; #define PG8_LDA(dst, b, h) do { _Pragma("unroll") for (int m = 0; m < 4; ++m) _Pragma("unroll") for (int k = 0; k < 2; ++k) dst[m][k] = *(const PG8_LAS bf16x8*)(lds + PG8_SA(b, h) + aoff + m * 2048 + k * 1024); } while (0)
; #define PG8_LDB(dst, b, h) do { _Pragma("unroll") for (int n = 0; n < 2; ++n) _Pragma("unroll") for (int k = 0; k < 2; ++k) dst[n][k] = *(const PG8_LAS bf16x8*)(lds + PG8_SB(b, h) + boff + n * 2048 + k * 1024); } while (0)
; #define PG8_MMA(ai, bj, At, Bt) do { __builtin_amdgcn_s_setprio(1); _Pragma("unroll") for (int m = 0; m < 4; ++m) _Pragma("unroll") for (int n = 0; n < 2; ++n) _Pragma("unroll") for (int k = 0; k < 2; ++k) \
;         acc[ai][bj][m][n] = __builtin_amdgcn_mfma_f32_16x16x32_bf16(Bt[n][k], At[m][k], acc[ai][bj][m][n], 0, 0, 0); __builtin_amdgcn_s_setprio(0); } while (0)
; #define PG8_WAIT_V(n) asm volatile("s_waitcnt vmcnt(" #n ")" ::: "memory")
; #define PG8_WAIT_L(n) asm volatile("s_waitcnt lgkmcnt(" #n ")" ::: "memory")
; #define PG8_BAR __builtin_amdgcn_s_barrier()
; #define PG8_SCHED __builtin_amdgcn_sched_barrier(0)
; template <class Epi, class Sched, bool ALIGN_EPI = false, bool SP2 = false>
; __device__ __forceinline__ void gemm_phase(PG8_LAS unsigned char* lds, const Gemm g, const Sched& S, const Epi& E) {
;     ...
;             const char* a2 = last ? nA : cA + (size_t)(t + 2) * kstep; const char* b2 = last ? nB : cB + (size_t)(t + 2) * kstep;
;             const char* a3 = a2 + kstep; const char* b3 = b2 + kstep;
;             if (last && has_next) S.a_ready(nxt);
;             if constexpr (SP2) {
;             PG8_LDB(B0, 0, 0); PG8_LDB(B1, 0, 1); PG8_SCHED; PG8_LDA(At, 0, 0); PG8_STAGE(PG8_SA(1, 1), a1 + hstep, voffA);
;             PG8_WAIT_V(8); PG8_WAIT_L(0); PG8_BAR; PG8_MMA(0, 0, At, B0); PG8_MMA(0, 1, At, B1); PG8_BAR; PG8_SCHED;
;             PG8_LDA(At, 0, 1); PG8_STAGE(PG8_SB(0, 0), b2, voffB); PG8_STAGE(PG8_SB(0, 1), b2 + hstepB, voffB); PG8_STAGE(PG8_SA(0, 0), a2, voffA);
.LBB0_658:
	ds_read_b128 v[160:163], v154
	ds_read_b128 v[164:167], v154 offset:1024
	ds_read_b128 v[168:171], v154 offset:2048
	ds_read_b128 v[172:175], v154 offset:3072
	ds_read_b128 v[178:181], v155
	ds_read_b128 v[182:185], v155 offset:1024
	ds_read_b128 v[186:189], v155 offset:2048
	ds_read_b128 v[190:193], v155 offset:3072
	s_add_u32 s22, s20, 0xfffc0080
	s_addc_u32 s23, s21, -1
	s_cmp_eq_u32 s49, 12
	s_cselect_b32 s25, s13, s23
	s_cselect_b32 s24, s45, s22
	s_cselect_b32 s23, s11, s48
	s_cselect_b32 s22, s46, s47
	v_lshl_add_u64 v[226:227], s[20:21], 0, v[138:139]
	s_add_i32 m0, s33, 0xc000
	ds_read_b128 v[194:197], v156
	ds_read_b128 v[198:201], v156 offset:1024
	ds_read_b128 v[202:205], v156 offset:2048
	ds_read_b128 v[206:209], v156 offset:3072
	ds_read_b128 v[210:213], v156 offset:4096
	ds_read_b128 v[214:217], v156 offset:5120
	ds_read_b128 v[218:221], v156 offset:6144
	ds_read_b128 v[222:225], v156 offset:7168
	global_load_lds_dwordx4 v[226:227], off
	v_lshl_add_u64 v[226:227], s[20:21], 0, v[140:141]
	s_add_i32 m0, s33, 0xe000
	s_nop 0
	global_load_lds_dwordx4 v[226:227], off
	s_waitcnt vmcnt(8)
	s_waitcnt lgkmcnt(0)
	s_barrier
	s_setprio 1
	v_mfma_f32_16x16x32_bf16 v[124:127], v[160:163], v[194:197], v[124:127]
	v_mfma_f32_16x16x32_bf16 v[120:123], v[168:171], v[194:197], v[120:123]
	v_mfma_f32_16x16x32_bf16 v[108:111], v[160:163], v[202:205], v[108:111]
	v_mfma_f32_16x16x32_bf16 v[104:107], v[168:171], v[202:205], v[104:107]
	v_mfma_f32_16x16x32_bf16 v[92:95], v[160:163], v[210:213], v[92:95]
	v_mfma_f32_16x16x32_bf16 v[88:91], v[168:171], v[210:213], v[88:91]
	v_mfma_f32_16x16x32_bf16 v[76:79], v[160:163], v[218:221], v[76:79]
	v_mfma_f32_16x16x32_bf16 v[72:75], v[168:171], v[218:221], v[72:75]
	v_mfma_f32_16x16x32_bf16 v[124:127], v[164:167], v[198:201], v[124:127]
	v_mfma_f32_16x16x32_bf16 v[120:123], v[172:175], v[198:201], v[120:123]
	v_mfma_f32_16x16x32_bf16 v[108:111], v[164:167], v[206:209], v[108:111]
	v_mfma_f32_16x16x32_bf16 v[104:107], v[172:175], v[206:209], v[104:107]
	v_mfma_f32_16x16x32_bf16 v[92:95], v[164:167], v[214:217], v[92:95]
	v_mfma_f32_16x16x32_bf16 v[88:91], v[172:175], v[214:217], v[88:91]
	v_mfma_f32_16x16x32_bf16 v[76:79], v[164:167], v[222:225], v[76:79]
	v_mfma_f32_16x16x32_bf16 v[72:75], v[172:175], v[222:225], v[72:75]
	s_setprio 0
	s_setprio 1
	v_mfma_f32_16x16x32_bf16 v[116:119], v[178:181], v[194:197], v[116:119]
	v_mfma_f32_16x16x32_bf16 v[112:115], v[186:189], v[194:197], v[112:115]
	v_mfma_f32_16x16x32_bf16 v[100:103], v[178:181], v[202:205], v[100:103]
	v_mfma_f32_16x16x32_bf16 v[96:99], v[186:189], v[202:205], v[96:99]
	v_mfma_f32_16x16x32_bf16 v[84:87], v[178:181], v[210:213], v[84:87]
	v_mfma_f32_16x16x32_bf16 v[80:83], v[186:189], v[210:213], v[80:83]
	v_mfma_f32_16x16x32_bf16 v[68:71], v[178:181], v[218:221], v[68:71]
	v_mfma_f32_16x16x32_bf16 v[64:67], v[186:189], v[218:221], v[64:67]
	v_mfma_f32_16x16x32_bf16 v[116:119], v[182:185], v[198:201], v[116:119]
	v_mfma_f32_16x16x32_bf16 v[112:115], v[190:193], v[198:201], v[112:115]
	v_mfma_f32_16x16x32_bf16 v[100:103], v[182:185], v[206:209], v[100:103]
	v_mfma_f32_16x16x32_bf16 v[96:99], v[190:193], v[206:209], v[96:99]
	v_mfma_f32_16x16x32_bf16 v[84:87], v[182:185], v[214:217], v[84:87]
	v_mfma_f32_16x16x32_bf16 v[80:83], v[190:193], v[214:217], v[80:83]
	v_mfma_f32_16x16x32_bf16 v[68:71], v[182:185], v[222:225], v[68:71]
	v_mfma_f32_16x16x32_bf16 v[64:67], v[190:193], v[222:225], v[64:67]
	s_setprio 0
	s_barrier
	s_add_i32 s50, s43, s31
	v_lshl_add_u64 v[226:227], s[22:23], 0, v[130:131]
	s_mov_b32 m0, s50
	ds_read_b128 v[194:197], v156 offset:16384
	ds_read_b128 v[198:201], v156 offset:17408
	ds_read_b128 v[202:205], v156 offset:18432
	ds_read_b128 v[206:209], v156 offset:19456
	ds_read_b128 v[210:213], v156 offset:20480
	ds_read_b128 v[214:217], v156 offset:21504
	ds_read_b128 v[218:221], v156 offset:22528
	ds_read_b128 v[222:225], v156 offset:23552
	global_load_lds_dwordx4 v[226:227], off
	s_add_i32 m0, s50, 0x2000
	s_add_u32 s50, s22, 0x10000
	v_lshl_add_u64 v[228:229], s[22:23], 0, v[134:135]
	s_addc_u32 s51, s23, 0
	s_add_i32 s52, s44, s31
	global_load_lds_dwordx4 v[228:229], off
	v_lshl_add_u64 v[230:231], s[50:51], 0, v[130:131]
	s_mov_b32 m0, s52
	v_lshl_add_u64 v[232:233], s[24:25], 0, v[132:133]
	global_load_lds_dwordx4 v[230:231], off
	v_lshl_add_u64 v[230:231], s[50:51], 0, v[134:135]
	s_add_i32 m0, s52, 0x2000
	s_nop 0
	global_load_lds_dwordx4 v[230:231], off
	v_lshl_add_u64 v[230:231], s[24:25], 0, v[128:129]
	s_mov_b32 m0, s33
	s_nop 0
	global_load_lds_dwordx4 v[230:231], off
	s_mov_b32 m0, s34
	s_nop 0
	global_load_lds_dwordx4 v[232:233], off
	s_waitcnt vmcnt(8)
	s_waitcnt lgkmcnt(0)
	s_barrier
; #define PG8_STAGE(bufoff, gbase, voff) do { _Pragma("unroll") for (int _i = 0; _i < 2; ++_i) \
;         __builtin_amdgcn_global_load_lds((const unsigned*)((const char*)(gbase) + (voff)[_i]), (PG8_LAS unsigned*)(lds + (bufoff) + ldsw + _i * 8192), 16, 0, 0); } while (0)
; #define PG8_LDA(dst, b, h) do { _Pragma("unroll") for (int m = 0; m < 4; ++m) _Pragma("unroll") for (int k = 0; k < 2; ++k) dst[m][k] = *(const PG8_LAS bf16x8*)(lds + PG8_SA(b, h) + aoff + m * 2048 + k * 1024); } while (0)
; #define PG8_LDB(dst, b, h) do { _Pragma("unroll") for (int n = 0; n < 2; ++n) _Pragma("unroll") for (int k = 0; k < 2; ++k) dst[n][k] = *(const PG8_LAS bf16x8*)(lds + PG8_SB(b, h) + boff + n * 2048 + k * 1024); } while (0)
; #define PG8_MMA(ai, bj, At, Bt) do { __builtin_amdgcn_s_setprio(1); _Pragma("unroll") for (int m = 0; m < 4; ++m) _Pragma("unroll") for (int n = 0; n < 2; ++n) _Pragma("unroll") for (int k = 0; k < 2; ++k) \
;         acc[ai][bj][m][n] = __builtin_amdgcn_mfma_f32_16x16x32_bf16(Bt[n][k], At[m][k], acc[ai][bj][m][n], 0, 0, 0); __builtin_amdgcn_s_setprio(0); } while (0)
; #define PG8_WAIT_V(n) asm volatile("s_waitcnt vmcnt(" #n ")" ::: "memory")
; #define PG8_WAIT_L(n) asm volatile("s_waitcnt lgkmcnt(" #n ")" ::: "memory")
; #define PG8_BAR __builtin_amdgcn_s_barrier()
; #define PG8_SCHED __builtin_amdgcn_sched_barrier(0)
; template <class Epi, class Sched, bool ALIGN_EPI = false, bool SP2 = false>
; __device__ __forceinline__ void gemm_phase(PG8_LAS unsigned char* lds, const Gemm g, const Sched& S, const Epi& E) {
;     ...
;             PG8_WAIT_V(8); PG8_WAIT_L(0); PG8_BAR; PG8_MMA(1, 0, At, B0); PG8_MMA(1, 1, At, B1); PG8_BAR; PG8_SCHED;
;             PG8_LDB(B0, 1, 0); PG8_LDB(B1, 1, 1); PG8_SCHED; PG8_LDA(At, 1, 0); PG8_STAGE(PG8_SA(0, 1), a2 + hstep, voffA);
;             PG8_WAIT_V(8); PG8_WAIT_L(0); PG8_BAR; PG8_MMA(0, 0, At, B0); PG8_MMA(0, 1, At, B1); PG8_BAR; PG8_SCHED;
	s_setprio 1
	v_mfma_f32_16x16x32_bf16 v[60:63], v[160:163], v[194:197], v[60:63]
	v_mfma_f32_16x16x32_bf16 v[56:59], v[168:171], v[194:197], v[56:59]
	v_mfma_f32_16x16x32_bf16 v[44:47], v[160:163], v[202:205], v[44:47]
	v_mfma_f32_16x16x32_bf16 v[40:43], v[168:171], v[202:205], v[40:43]
	v_mfma_f32_16x16x32_bf16 v[28:31], v[160:163], v[210:213], v[28:31]
	v_mfma_f32_16x16x32_bf16 v[24:27], v[168:171], v[210:213], v[24:27]
	v_mfma_f32_16x16x32_bf16 v[12:15], v[160:163], v[218:221], v[12:15]
	v_mfma_f32_16x16x32_bf16 v[8:11], v[168:171], v[218:221], v[8:11]
	v_mfma_f32_16x16x32_bf16 v[60:63], v[164:167], v[198:201], v[60:63]
	v_mfma_f32_16x16x32_bf16 v[56:59], v[172:175], v[198:201], v[56:59]
	v_mfma_f32_16x16x32_bf16 v[44:47], v[164:167], v[206:209], v[44:47]
	v_mfma_f32_16x16x32_bf16 v[40:43], v[172:175], v[206:209], v[40:43]
	v_mfma_f32_16x16x32_bf16 v[28:31], v[164:167], v[214:217], v[28:31]
	v_mfma_f32_16x16x32_bf16 v[24:27], v[172:175], v[214:217], v[24:27]
	v_mfma_f32_16x16x32_bf16 v[12:15], v[164:167], v[222:225], v[12:15]
	v_mfma_f32_16x16x32_bf16 v[8:11], v[172:175], v[222:225], v[8:11]
	s_setprio 0
	s_setprio 1
	v_mfma_f32_16x16x32_bf16 v[52:55], v[178:181], v[194:197], v[52:55]
	v_mfma_f32_16x16x32_bf16 v[48:51], v[186:189], v[194:197], v[48:51]
	v_mfma_f32_16x16x32_bf16 v[36:39], v[178:181], v[202:205], v[36:39]
	v_mfma_f32_16x16x32_bf16 v[32:35], v[186:189], v[202:205], v[32:35]
	v_mfma_f32_16x16x32_bf16 v[20:23], v[178:181], v[210:213], v[20:23]
	v_mfma_f32_16x16x32_bf16 v[16:19], v[186:189], v[210:213], v[16:19]
	v_mfma_f32_16x16x32_bf16 v[4:7], v[178:181], v[218:221], v[4:7]
	v_mfma_f32_16x16x32_bf16 v[0:3], v[186:189], v[218:221], v[0:3]
	v_mfma_f32_16x16x32_bf16 v[52:55], v[182:185], v[198:201], v[52:55]
	v_mfma_f32_16x16x32_bf16 v[48:51], v[190:193], v[198:201], v[48:51]
	v_mfma_f32_16x16x32_bf16 v[36:39], v[182:185], v[206:209], v[36:39]
	v_mfma_f32_16x16x32_bf16 v[32:35], v[190:193], v[206:209], v[32:35]
	v_mfma_f32_16x16x32_bf16 v[20:23], v[182:185], v[214:217], v[20:23]
	v_mfma_f32_16x16x32_bf16 v[16:19], v[190:193], v[214:217], v[16:19]
	v_mfma_f32_16x16x32_bf16 v[4:7], v[182:185], v[222:225], v[4:7]
	v_mfma_f32_16x16x32_bf16 v[0:3], v[190:193], v[222:225], v[0:3]
	s_setprio 0
	s_barrier
	s_add_i32 s50, 0, 0x18000
	v_add_u32_e32 v149, s50, v152
	s_add_i32 s51, 0, 0x1c000
	ds_read_b128 v[160:163], v149
	ds_read_b128 v[164:167], v149 offset:1024
	ds_read_b128 v[168:171], v149 offset:2048
	ds_read_b128 v[172:175], v149 offset:3072
	v_add_u32_e32 v149, s51, v152
	ds_read_b128 v[178:181], v149
	ds_read_b128 v[182:185], v149 offset:1024
	ds_read_b128 v[186:189], v149 offset:2048
	ds_read_b128 v[190:193], v149 offset:3072
	s_add_u32 s24, s24, 0x40000
	s_addc_u32 s25, s25, 0
	s_mov_b32 m0, s35
	v_lshl_add_u64 v[234:235], s[24:25], 0, v[128:129]
	ds_read_b128 v[194:197], v156 offset:32768
	ds_read_b128 v[198:201], v156 offset:33792
	ds_read_b128 v[202:205], v156 offset:34816
	ds_read_b128 v[206:209], v156 offset:35840
	ds_read_b128 v[210:213], v156 offset:36864
	ds_read_b128 v[214:217], v156 offset:37888
	ds_read_b128 v[218:221], v156 offset:38912
	ds_read_b128 v[222:225], v156 offset:39936
	global_load_lds_dwordx4 v[234:235], off
	v_lshl_add_u64 v[234:235], s[24:25], 0, v[132:133]
	s_mov_b32 m0, s36
	s_nop 0
	global_load_lds_dwordx4 v[234:235], off
	s_waitcnt vmcnt(8)
	s_waitcnt lgkmcnt(0)
	s_barrier
	s_setprio 1
	v_mfma_f32_16x16x32_bf16 v[124:127], v[160:163], v[194:197], v[124:127]
	v_mfma_f32_16x16x32_bf16 v[120:123], v[168:171], v[194:197], v[120:123]
	v_mfma_f32_16x16x32_bf16 v[108:111], v[160:163], v[202:205], v[108:111]
	v_mfma_f32_16x16x32_bf16 v[104:107], v[168:171], v[202:205], v[104:107]
	v_mfma_f32_16x16x32_bf16 v[92:95], v[160:163], v[210:213], v[92:95]
	v_mfma_f32_16x16x32_bf16 v[88:91], v[168:171], v[210:213], v[88:91]
	v_mfma_f32_16x16x32_bf16 v[76:79], v[160:163], v[218:221], v[76:79]
	v_mfma_f32_16x16x32_bf16 v[72:75], v[168:171], v[218:221], v[72:75]
	v_mfma_f32_16x16x32_bf16 v[124:127], v[164:167], v[198:201], v[124:127]
	v_mfma_f32_16x16x32_bf16 v[120:123], v[172:175], v[198:201], v[120:123]
	v_mfma_f32_16x16x32_bf16 v[108:111], v[164:167], v[206:209], v[108:111]
	v_mfma_f32_16x16x32_bf16 v[104:107], v[172:175], v[206:209], v[104:107]
	v_mfma_f32_16x16x32_bf16 v[92:95], v[164:167], v[214:217], v[92:95]
	v_mfma_f32_16x16x32_bf16 v[88:91], v[172:175], v[214:217], v[88:91]
	v_mfma_f32_16x16x32_bf16 v[76:79], v[164:167], v[222:225], v[76:79]
	v_mfma_f32_16x16x32_bf16 v[72:75], v[172:175], v[222:225], v[72:75]
	s_setprio 0
	s_setprio 1
	v_mfma_f32_16x16x32_bf16 v[116:119], v[178:181], v[194:197], v[116:119]
	v_mfma_f32_16x16x32_bf16 v[112:115], v[186:189], v[194:197], v[112:115]
	v_mfma_f32_16x16x32_bf16 v[100:103], v[178:181], v[202:205], v[100:103]
	v_mfma_f32_16x16x32_bf16 v[96:99], v[186:189], v[202:205], v[96:99]
	v_mfma_f32_16x16x32_bf16 v[84:87], v[178:181], v[210:213], v[84:87]
	v_mfma_f32_16x16x32_bf16 v[80:83], v[186:189], v[210:213], v[80:83]
	v_mfma_f32_16x16x32_bf16 v[68:71], v[178:181], v[218:221], v[68:71]
	v_mfma_f32_16x16x32_bf16 v[64:67], v[186:189], v[218:221], v[64:67]
	v_mfma_f32_16x16x32_bf16 v[116:119], v[182:185], v[198:201], v[116:119]
	v_mfma_f32_16x16x32_bf16 v[112:115], v[190:193], v[198:201], v[112:115]
	v_mfma_f32_16x16x32_bf16 v[100:103], v[182:185], v[206:209], v[100:103]
	v_mfma_f32_16x16x32_bf16 v[96:99], v[190:193], v[206:209], v[96:99]
	v_mfma_f32_16x16x32_bf16 v[84:87], v[182:185], v[214:217], v[84:87]
	v_mfma_f32_16x16x32_bf16 v[80:83], v[190:193], v[214:217], v[80:83]
	v_mfma_f32_16x16x32_bf16 v[68:71], v[182:185], v[222:225], v[68:71]
	v_mfma_f32_16x16x32_bf16 v[64:67], v[190:193], v[222:225], v[64:67]
	s_setprio 0
	s_barrier
; #define PG8_STAGE(bufoff, gbase, voff) do { _Pragma("unroll") for (int _i = 0; _i < 2; ++_i) \
;         __builtin_amdgcn_global_load_lds((const unsigned*)((const char*)(gbase) + (voff)[_i]), (PG8_LAS unsigned*)(lds + (bufoff) + ldsw + _i * 8192), 16, 0, 0); } while (0)
; #define PG8_LDA(dst, b, h) do { _Pragma("unroll") for (int m = 0; m < 4; ++m) _Pragma("unroll") for (int k = 0; k < 2; ++k) dst[m][k] = *(const PG8_LAS bf16x8*)(lds + PG8_SA(b, h) + aoff + m * 2048 + k * 1024); } while (0)
; #define PG8_MMA(ai, bj, At, Bt) do { __builtin_amdgcn_s_setprio(1); _Pragma("unroll") for (int m = 0; m < 4; ++m) _Pragma("unroll") for (int n = 0; n < 2; ++n) _Pragma("unroll") for (int k = 0; k < 2; ++k) \
;         acc[ai][bj][m][n] = __builtin_amdgcn_mfma_f32_16x16x32_bf16(Bt[n][k], At[m][k], acc[ai][bj][m][n], 0, 0, 0); __builtin_amdgcn_s_setprio(0); } while (0)
; #define PG8_WAIT_V(n) asm volatile("s_waitcnt vmcnt(" #n ")" ::: "memory")
; #define PG8_WAIT_L(n) asm volatile("s_waitcnt lgkmcnt(" #n ")" ::: "memory")
; #define PG8_BAR __builtin_amdgcn_s_barrier()
; #define PG8_SCHED __builtin_amdgcn_sched_barrier(0)
; template <class Epi, class Sched, bool ALIGN_EPI = false, bool SP2 = false>
; __device__ __forceinline__ void gemm_phase(PG8_LAS unsigned char* lds, const Gemm g, const Sched& S, const Epi& E) {
;     ...
;             PG8_LDA(At, 1, 1); PG8_STAGE(PG8_SB(1, 0), b3, voffB); PG8_STAGE(PG8_SB(1, 1), b3 + hstepB, voffB); PG8_STAGE(PG8_SA(1, 0), a3, voffA);
;             PG8_WAIT_V(8); PG8_WAIT_L(0); PG8_BAR; PG8_MMA(1, 0, At, B0); PG8_MMA(1, 1, At, B1); PG8_BAR; PG8_SCHED;
;     ...
;         if constexpr (ALIGN_EPI) { if (wr == 0) PG8_BAR; }
	s_add_i32 s24, s50, s31
	v_lshl_add_u64 v[226:227], v[226:227], 0, s[6:7]
	s_mov_b32 m0, s24
	ds_read_b128 v[194:197], v156 offset:49152
	ds_read_b128 v[198:201], v156 offset:50176
	ds_read_b128 v[202:205], v156 offset:51200
	ds_read_b128 v[206:209], v156 offset:52224
	ds_read_b128 v[210:213], v156 offset:53248
	ds_read_b128 v[214:217], v156 offset:54272
	ds_read_b128 v[218:221], v156 offset:55296
	ds_read_b128 v[222:225], v156 offset:56320
	global_load_lds_dwordx4 v[226:227], off
	s_add_i32 m0, s24, 0x2000
	s_add_u32 s22, s22, 0x10080
	v_lshl_add_u64 v[226:227], v[228:229], 0, s[6:7]
	s_addc_u32 s23, s23, 0
	s_add_i32 s24, s51, s31
	global_load_lds_dwordx4 v[226:227], off
	v_lshl_add_u64 v[226:227], s[22:23], 0, v[130:131]
	s_mov_b32 m0, s24
	s_nop 0
	global_load_lds_dwordx4 v[226:227], off
	v_lshl_add_u64 v[226:227], s[22:23], 0, v[134:135]
	s_add_i32 m0, s24, 0x2000
	s_nop 0
	global_load_lds_dwordx4 v[226:227], off
	v_lshl_add_u64 v[226:227], v[230:231], 0, s[6:7]
	s_mov_b32 m0, s39
	s_nop 0
	global_load_lds_dwordx4 v[226:227], off
	v_lshl_add_u64 v[226:227], v[232:233], 0, s[6:7]
	s_mov_b32 m0, s40
	s_nop 0
	global_load_lds_dwordx4 v[226:227], off
	s_waitcnt vmcnt(8)
	s_waitcnt lgkmcnt(0)
	s_barrier
	s_setprio 1
	v_mfma_f32_16x16x32_bf16 v[60:63], v[160:163], v[194:197], v[60:63]
	v_mfma_f32_16x16x32_bf16 v[56:59], v[168:171], v[194:197], v[56:59]
	v_mfma_f32_16x16x32_bf16 v[44:47], v[160:163], v[202:205], v[44:47]
	v_mfma_f32_16x16x32_bf16 v[40:43], v[168:171], v[202:205], v[40:43]
	v_mfma_f32_16x16x32_bf16 v[28:31], v[160:163], v[210:213], v[28:31]
	v_mfma_f32_16x16x32_bf16 v[24:27], v[168:171], v[210:213], v[24:27]
	v_mfma_f32_16x16x32_bf16 v[12:15], v[160:163], v[218:221], v[12:15]
	v_mfma_f32_16x16x32_bf16 v[8:11], v[168:171], v[218:221], v[8:11]
	v_mfma_f32_16x16x32_bf16 v[60:63], v[164:167], v[198:201], v[60:63]
	v_mfma_f32_16x16x32_bf16 v[56:59], v[172:175], v[198:201], v[56:59]
	v_mfma_f32_16x16x32_bf16 v[44:47], v[164:167], v[206:209], v[44:47]
	v_mfma_f32_16x16x32_bf16 v[40:43], v[172:175], v[206:209], v[40:43]
	v_mfma_f32_16x16x32_bf16 v[28:31], v[164:167], v[214:217], v[28:31]
	v_mfma_f32_16x16x32_bf16 v[24:27], v[172:175], v[214:217], v[24:27]
	v_mfma_f32_16x16x32_bf16 v[12:15], v[164:167], v[222:225], v[12:15]
	v_mfma_f32_16x16x32_bf16 v[8:11], v[172:175], v[222:225], v[8:11]
	s_setprio 0
	s_setprio 1
	v_mfma_f32_16x16x32_bf16 v[52:55], v[178:181], v[194:197], v[52:55]
	v_mfma_f32_16x16x32_bf16 v[48:51], v[186:189], v[194:197], v[48:51]
	v_mfma_f32_16x16x32_bf16 v[36:39], v[178:181], v[202:205], v[36:39]
	v_mfma_f32_16x16x32_bf16 v[32:35], v[186:189], v[202:205], v[32:35]
	v_mfma_f32_16x16x32_bf16 v[20:23], v[178:181], v[210:213], v[20:23]
	v_mfma_f32_16x16x32_bf16 v[16:19], v[186:189], v[210:213], v[16:19]
	v_mfma_f32_16x16x32_bf16 v[4:7], v[178:181], v[218:221], v[4:7]
	v_mfma_f32_16x16x32_bf16 v[0:3], v[186:189], v[218:221], v[0:3]
	v_mfma_f32_16x16x32_bf16 v[52:55], v[182:185], v[198:201], v[52:55]
	v_mfma_f32_16x16x32_bf16 v[48:51], v[190:193], v[198:201], v[48:51]
	v_mfma_f32_16x16x32_bf16 v[36:39], v[182:185], v[206:209], v[36:39]
	v_mfma_f32_16x16x32_bf16 v[32:35], v[190:193], v[206:209], v[32:35]
	v_mfma_f32_16x16x32_bf16 v[20:23], v[182:185], v[214:217], v[20:23]
	v_mfma_f32_16x16x32_bf16 v[16:19], v[190:193], v[214:217], v[16:19]
	v_mfma_f32_16x16x32_bf16 v[4:7], v[182:185], v[222:225], v[4:7]
	v_mfma_f32_16x16x32_bf16 v[0:3], v[190:193], v[222:225], v[0:3]
	s_setprio 0
	s_barrier
	s_add_i32 s49, s49, 2
	s_add_u32 s20, s20, 0x100
	s_addc_u32 s21, s21, 0
	s_add_u32 s47, s47, 0x100
	s_addc_u32 s48, s48, 0
	s_cmp_gt_u32 s49, 13
	s_cbranch_scc0 .LBB0_658
	s_and_b64 vcc, exec, s[8:9]
	s_cbranch_vccz .LBB0_661
	s_barrier

; #define PG8_STAGE(bufoff, gbase, voff) do { _Pragma("unroll") for (int _i = 0; _i < 2; ++_i) \
;         __builtin_amdgcn_global_load_lds((const unsigned*)((const char*)(gbase) + (voff)[_i]), (PG8_LAS unsigned*)(lds + (bufoff) + ldsw + _i * 8192), 16, 0, 0); } while (0)
; #define PG8_LDA(dst, b, h) do { _Pragma("unroll") for (int m = 0; m < 4; ++m) _Pragma("unroll") for (int k = 0; k < 2; ++k) dst[m][k] = *(const PG8_LAS bf16x8*)(lds + PG8_SA(b, h) + aoff + m * 2048 + k * 1024); } while (0)
; #define PG8_LDB(dst, b, h) do { _Pragma("unroll") for (int n = 0; n < 2; ++n) _Pragma("unroll") for (int k = 0; k < 2; ++k) dst[n][k] = *(const PG8_LAS bf16x8*)(lds + PG8_SB(b, h) + boff + n * 2048 + k * 1024); } while (0)
; #define PG8_MMA(ai, bj, At, Bt) do { __builtin_amdgcn_s_setprio(1); _Pragma("unroll") for (int m = 0; m < 4; ++m) _Pragma("unroll") for (int n = 0; n < 2; ++n) _Pragma("unroll") for (int k = 0; k < 2; ++k) \
;         acc[ai][bj][m][n] = __builtin_amdgcn_mfma_f32_16x16x32_bf16(Bt[n][k], At[m][k], acc[ai][bj][m][n], 0, 0, 0); __builtin_amdgcn_s_setprio(0); } while (0)
; #define PG8_WAIT_V(n) asm volatile("s_waitcnt vmcnt(" #n ")" ::: "memory")
; #define PG8_WAIT_L(n) asm volatile("s_waitcnt lgkmcnt(" #n ")" ::: "memory")
; #define PG8_BAR __builtin_amdgcn_s_barrier()
; #define PG8_SCHED __builtin_amdgcn_sched_barrier(0)
; template <class Epi, class Sched, bool ALIGN_EPI = false, bool SP2 = false>
; __device__ __forceinline__ void gemm_phase(PG8_LAS unsigned char* lds, const Gemm g, const Sched& S, const Epi& E) {
;     ...
;             const char* a2 = last ? nA : cA + (size_t)(t + 2) * kstep; const char* b2 = last ? nB : cB + (size_t)(t + 2) * kstep;
;             const char* a3 = a2 + kstep; const char* b3 = b2 + kstep;
;             if (last && has_next) S.a_ready(nxt);
;             if constexpr (SP2) {
;             PG8_LDB(B0, 0, 0); PG8_LDB(B1, 0, 1); PG8_SCHED; PG8_LDA(At, 0, 0); PG8_STAGE(PG8_SA(1, 1), a1 + hstep, voffA);
;             PG8_WAIT_V(8); PG8_WAIT_L(0); PG8_BAR; PG8_MMA(0, 0, At, B0); PG8_MMA(0, 1, At, B1); PG8_BAR; PG8_SCHED;
;             PG8_LDA(At, 0, 1); PG8_STAGE(PG8_SB(0, 0), b2, voffB); PG8_STAGE(PG8_SB(0, 1), b2 + hstepB, voffB); PG8_STAGE(PG8_SA(0, 0), a2, voffA);
.LBB0_737:
	ds_read_b128 v[154:157], v168
	ds_read_b128 v[158:161], v168 offset:1024
	ds_read_b128 v[178:181], v168 offset:2048
	ds_read_b128 v[182:185], v168 offset:3072
	ds_read_b128 v[186:189], v169
	ds_read_b128 v[190:193], v169 offset:1024
	ds_read_b128 v[194:197], v169 offset:2048
	ds_read_b128 v[198:201], v169 offset:3072
	s_add_u32 s38, s36, 0xfff00080
	s_addc_u32 s39, s37, -1
	s_cmp_eq_u32 s60, 60
	s_cselect_b32 s41, s27, s39
	s_cselect_b32 s40, s56, s38
	s_cselect_b32 s39, s25, s59
	s_cselect_b32 s38, s57, s58
	v_lshl_add_u64 v[162:163], s[36:37], 0, v[138:139]
	s_add_i32 m0, s35, 0xc000
	ds_read_b128 v[202:205], v170
	ds_read_b128 v[206:209], v170 offset:1024
	ds_read_b128 v[210:213], v170 offset:2048
	ds_read_b128 v[214:217], v170 offset:3072
	ds_read_b128 v[218:221], v170 offset:4096
	ds_read_b128 v[222:225], v170 offset:5120
	ds_read_b128 v[226:229], v170 offset:6144
	ds_read_b128 v[230:233], v170 offset:7168
	global_load_lds_dwordx4 v[162:163], off
	v_lshl_add_u64 v[162:163], s[36:37], 0, v[140:141]
	s_add_i32 m0, s35, 0xe000
	s_nop 0
	global_load_lds_dwordx4 v[162:163], off
	s_waitcnt vmcnt(8)
	s_waitcnt lgkmcnt(0)
	s_barrier
	s_setprio 1
	v_mfma_f32_16x16x32_bf16 v[124:127], v[154:157], v[202:205], v[124:127]
	v_mfma_f32_16x16x32_bf16 v[120:123], v[178:181], v[202:205], v[120:123]
	v_mfma_f32_16x16x32_bf16 v[116:119], v[154:157], v[210:213], v[116:119]
	v_mfma_f32_16x16x32_bf16 v[104:107], v[178:181], v[210:213], v[104:107]
	v_mfma_f32_16x16x32_bf16 v[92:95], v[154:157], v[218:221], v[92:95]
	v_mfma_f32_16x16x32_bf16 v[88:91], v[178:181], v[218:221], v[88:91]
	v_mfma_f32_16x16x32_bf16 v[76:79], v[154:157], v[226:229], v[76:79]
	v_mfma_f32_16x16x32_bf16 v[72:75], v[178:181], v[226:229], v[72:75]
	v_mfma_f32_16x16x32_bf16 v[124:127], v[158:161], v[206:209], v[124:127]
	v_mfma_f32_16x16x32_bf16 v[120:123], v[182:185], v[206:209], v[120:123]
	v_mfma_f32_16x16x32_bf16 v[116:119], v[158:161], v[214:217], v[116:119]
	v_mfma_f32_16x16x32_bf16 v[104:107], v[182:185], v[214:217], v[104:107]
	v_mfma_f32_16x16x32_bf16 v[92:95], v[158:161], v[222:225], v[92:95]
	v_mfma_f32_16x16x32_bf16 v[88:91], v[182:185], v[222:225], v[88:91]
	v_mfma_f32_16x16x32_bf16 v[76:79], v[158:161], v[230:233], v[76:79]
	v_mfma_f32_16x16x32_bf16 v[72:75], v[182:185], v[230:233], v[72:75]
	s_setprio 0
	s_setprio 1
	v_mfma_f32_16x16x32_bf16 v[112:115], v[186:189], v[202:205], v[112:115]
	v_mfma_f32_16x16x32_bf16 v[108:111], v[194:197], v[202:205], v[108:111]
	v_mfma_f32_16x16x32_bf16 v[100:103], v[186:189], v[210:213], v[100:103]
	v_mfma_f32_16x16x32_bf16 v[96:99], v[194:197], v[210:213], v[96:99]
	v_mfma_f32_16x16x32_bf16 v[84:87], v[186:189], v[218:221], v[84:87]
	v_mfma_f32_16x16x32_bf16 v[80:83], v[194:197], v[218:221], v[80:83]
	v_mfma_f32_16x16x32_bf16 v[68:71], v[186:189], v[226:229], v[68:71]
	v_mfma_f32_16x16x32_bf16 v[64:67], v[194:197], v[226:229], v[64:67]
	v_mfma_f32_16x16x32_bf16 v[112:115], v[190:193], v[206:209], v[112:115]
	v_mfma_f32_16x16x32_bf16 v[108:111], v[198:201], v[206:209], v[108:111]
	v_mfma_f32_16x16x32_bf16 v[100:103], v[190:193], v[214:217], v[100:103]
	v_mfma_f32_16x16x32_bf16 v[96:99], v[198:201], v[214:217], v[96:99]
	v_mfma_f32_16x16x32_bf16 v[84:87], v[190:193], v[222:225], v[84:87]
	v_mfma_f32_16x16x32_bf16 v[80:83], v[198:201], v[222:225], v[80:83]
	v_mfma_f32_16x16x32_bf16 v[68:71], v[190:193], v[230:233], v[68:71]
	v_mfma_f32_16x16x32_bf16 v[64:67], v[198:201], v[230:233], v[64:67]
	s_setprio 0
	s_barrier
	s_add_i32 s61, s53, s44
	v_lshl_add_u64 v[162:163], s[38:39], 0, v[130:131]
	s_mov_b32 m0, s61
	ds_read_b128 v[202:205], v170 offset:16384
	ds_read_b128 v[206:209], v170 offset:17408
	ds_read_b128 v[210:213], v170 offset:18432
	ds_read_b128 v[214:217], v170 offset:19456
	ds_read_b128 v[218:221], v170 offset:20480
	ds_read_b128 v[222:225], v170 offset:21504
	ds_read_b128 v[226:229], v170 offset:22528
	ds_read_b128 v[230:233], v170 offset:23552
	global_load_lds_dwordx4 v[162:163], off
	s_add_i32 m0, s61, 0x2000
	s_add_u32 s62, s38, 0x40000
	v_lshl_add_u64 v[174:175], s[38:39], 0, v[134:135]
	s_addc_u32 s63, s39, 0
	s_add_i32 s61, s54, s44
	global_load_lds_dwordx4 v[174:175], off
	v_lshl_add_u64 v[234:235], s[62:63], 0, v[130:131]
	s_mov_b32 m0, s61
	v_lshl_add_u64 v[236:237], s[40:41], 0, v[132:133]
	global_load_lds_dwordx4 v[234:235], off
	v_lshl_add_u64 v[234:235], s[62:63], 0, v[134:135]
	s_add_i32 m0, s61, 0x2000
	s_nop 0
	global_load_lds_dwordx4 v[234:235], off
	v_lshl_add_u64 v[234:235], s[40:41], 0, v[128:129]
	s_mov_b32 m0, s35
	s_nop 0
	global_load_lds_dwordx4 v[234:235], off
	s_mov_b32 m0, s45
	s_nop 0
	global_load_lds_dwordx4 v[236:237], off
	s_waitcnt vmcnt(8)
	s_waitcnt lgkmcnt(0)
	s_barrier
; #define PG8_STAGE(bufoff, gbase, voff) do { _Pragma("unroll") for (int _i = 0; _i < 2; ++_i) \
;         __builtin_amdgcn_global_load_lds((const unsigned*)((const char*)(gbase) + (voff)[_i]), (PG8_LAS unsigned*)(lds + (bufoff) + ldsw + _i * 8192), 16, 0, 0); } while (0)
; #define PG8_LDA(dst, b, h) do { _Pragma("unroll") for (int m = 0; m < 4; ++m) _Pragma("unroll") for (int k = 0; k < 2; ++k) dst[m][k] = *(const PG8_LAS bf16x8*)(lds + PG8_SA(b, h) + aoff + m * 2048 + k * 1024); } while (0)
; #define PG8_LDB(dst, b, h) do { _Pragma("unroll") for (int n = 0; n < 2; ++n) _Pragma("unroll") for (int k = 0; k < 2; ++k) dst[n][k] = *(const PG8_LAS bf16x8*)(lds + PG8_SB(b, h) + boff + n * 2048 + k * 1024); } while (0)
; #define PG8_MMA(ai, bj, At, Bt) do { __builtin_amdgcn_s_setprio(1); _Pragma("unroll") for (int m = 0; m < 4; ++m) _Pragma("unroll") for (int n = 0; n < 2; ++n) _Pragma("unroll") for (int k = 0; k < 2; ++k) \
;         acc[ai][bj][m][n] = __builtin_amdgcn_mfma_f32_16x16x32_bf16(Bt[n][k], At[m][k], acc[ai][bj][m][n], 0, 0, 0); __builtin_amdgcn_s_setprio(0); } while (0)
; #define PG8_WAIT_V(n) asm volatile("s_waitcnt vmcnt(" #n ")" ::: "memory")
; #define PG8_WAIT_L(n) asm volatile("s_waitcnt lgkmcnt(" #n ")" ::: "memory")
; #define PG8_BAR __builtin_amdgcn_s_barrier()
; #define PG8_SCHED __builtin_amdgcn_sched_barrier(0)
; template <class Epi, class Sched, bool ALIGN_EPI = false, bool SP2 = false>
; __device__ __forceinline__ void gemm_phase(PG8_LAS unsigned char* lds, const Gemm g, const Sched& S, const Epi& E) {
;     ...
;             PG8_WAIT_V(8); PG8_WAIT_L(0); PG8_BAR; PG8_MMA(1, 0, At, B0); PG8_MMA(1, 1, At, B1); PG8_BAR; PG8_SCHED;
;             PG8_LDB(B0, 1, 0); PG8_LDB(B1, 1, 1); PG8_SCHED; PG8_LDA(At, 1, 0); PG8_STAGE(PG8_SA(0, 1), a2 + hstep, voffA);
;             PG8_WAIT_V(8); PG8_WAIT_L(0); PG8_BAR; PG8_MMA(0, 0, At, B0); PG8_MMA(0, 1, At, B1); PG8_BAR; PG8_SCHED;
	s_setprio 1
	v_mfma_f32_16x16x32_bf16 v[60:63], v[154:157], v[202:205], v[60:63]
	v_mfma_f32_16x16x32_bf16 v[56:59], v[178:181], v[202:205], v[56:59]
	v_mfma_f32_16x16x32_bf16 v[44:47], v[154:157], v[210:213], v[44:47]
	v_mfma_f32_16x16x32_bf16 v[40:43], v[178:181], v[210:213], v[40:43]
	v_mfma_f32_16x16x32_bf16 v[28:31], v[154:157], v[218:221], v[28:31]
	v_mfma_f32_16x16x32_bf16 v[24:27], v[178:181], v[218:221], v[24:27]
	v_mfma_f32_16x16x32_bf16 v[12:15], v[154:157], v[226:229], v[12:15]
	v_mfma_f32_16x16x32_bf16 v[8:11], v[178:181], v[226:229], v[8:11]
	v_mfma_f32_16x16x32_bf16 v[60:63], v[158:161], v[206:209], v[60:63]
	v_mfma_f32_16x16x32_bf16 v[56:59], v[182:185], v[206:209], v[56:59]
	v_mfma_f32_16x16x32_bf16 v[44:47], v[158:161], v[214:217], v[44:47]
	v_mfma_f32_16x16x32_bf16 v[40:43], v[182:185], v[214:217], v[40:43]
	v_mfma_f32_16x16x32_bf16 v[28:31], v[158:161], v[222:225], v[28:31]
	v_mfma_f32_16x16x32_bf16 v[24:27], v[182:185], v[222:225], v[24:27]
	v_mfma_f32_16x16x32_bf16 v[12:15], v[158:161], v[230:233], v[12:15]
	v_mfma_f32_16x16x32_bf16 v[8:11], v[182:185], v[230:233], v[8:11]
	s_setprio 0
	s_setprio 1
	v_mfma_f32_16x16x32_bf16 v[52:55], v[186:189], v[202:205], v[52:55]
	v_mfma_f32_16x16x32_bf16 v[48:51], v[194:197], v[202:205], v[48:51]
	v_mfma_f32_16x16x32_bf16 v[36:39], v[186:189], v[210:213], v[36:39]
	v_mfma_f32_16x16x32_bf16 v[32:35], v[194:197], v[210:213], v[32:35]
	v_mfma_f32_16x16x32_bf16 v[20:23], v[186:189], v[218:221], v[20:23]
	v_mfma_f32_16x16x32_bf16 v[16:19], v[194:197], v[218:221], v[16:19]
	v_mfma_f32_16x16x32_bf16 v[4:7], v[186:189], v[226:229], v[4:7]
	v_mfma_f32_16x16x32_bf16 v[0:3], v[194:197], v[226:229], v[0:3]
	v_mfma_f32_16x16x32_bf16 v[52:55], v[190:193], v[206:209], v[52:55]
	v_mfma_f32_16x16x32_bf16 v[48:51], v[198:201], v[206:209], v[48:51]
	v_mfma_f32_16x16x32_bf16 v[36:39], v[190:193], v[214:217], v[36:39]
	v_mfma_f32_16x16x32_bf16 v[32:35], v[198:201], v[214:217], v[32:35]
	v_mfma_f32_16x16x32_bf16 v[20:23], v[190:193], v[222:225], v[20:23]
	v_mfma_f32_16x16x32_bf16 v[16:19], v[198:201], v[222:225], v[16:19]
	v_mfma_f32_16x16x32_bf16 v[4:7], v[190:193], v[230:233], v[4:7]
	v_mfma_f32_16x16x32_bf16 v[0:3], v[198:201], v[230:233], v[0:3]
	s_setprio 0
	s_barrier
	s_add_i32 s61, 0, 0x18000
	v_add_u32_e32 v151, s61, v166
	s_add_i32 s62, 0, 0x1c000
	ds_read_b128 v[154:157], v151
	ds_read_b128 v[158:161], v151 offset:1024
	ds_read_b128 v[178:181], v151 offset:2048
	ds_read_b128 v[182:185], v151 offset:3072
	v_add_u32_e32 v151, s62, v166
	ds_read_b128 v[186:189], v151
	ds_read_b128 v[190:193], v151 offset:1024
	ds_read_b128 v[194:197], v151 offset:2048
	ds_read_b128 v[198:201], v151 offset:3072
	s_add_u32 s40, s40, 0x100000
	s_addc_u32 s41, s41, 0
	s_mov_b32 m0, s46
	v_lshl_add_u64 v[238:239], s[40:41], 0, v[128:129]
	ds_read_b128 v[202:205], v170 offset:32768
	ds_read_b128 v[206:209], v170 offset:33792
	ds_read_b128 v[210:213], v170 offset:34816
	ds_read_b128 v[214:217], v170 offset:35840
	ds_read_b128 v[218:221], v170 offset:36864
	ds_read_b128 v[222:225], v170 offset:37888
	ds_read_b128 v[226:229], v170 offset:38912
	ds_read_b128 v[230:233], v170 offset:39936
	global_load_lds_dwordx4 v[238:239], off
	v_lshl_add_u64 v[238:239], s[40:41], 0, v[132:133]
	s_mov_b32 m0, s47
	s_nop 0
	global_load_lds_dwordx4 v[238:239], off
	s_waitcnt vmcnt(8)
	s_waitcnt lgkmcnt(0)
	s_barrier
	s_setprio 1
	v_mfma_f32_16x16x32_bf16 v[124:127], v[154:157], v[202:205], v[124:127]
	v_mfma_f32_16x16x32_bf16 v[120:123], v[178:181], v[202:205], v[120:123]
	v_mfma_f32_16x16x32_bf16 v[116:119], v[154:157], v[210:213], v[116:119]
	v_mfma_f32_16x16x32_bf16 v[104:107], v[178:181], v[210:213], v[104:107]
	v_mfma_f32_16x16x32_bf16 v[92:95], v[154:157], v[218:221], v[92:95]
	v_mfma_f32_16x16x32_bf16 v[88:91], v[178:181], v[218:221], v[88:91]
	v_mfma_f32_16x16x32_bf16 v[76:79], v[154:157], v[226:229], v[76:79]
	v_mfma_f32_16x16x32_bf16 v[72:75], v[178:181], v[226:229], v[72:75]
	v_mfma_f32_16x16x32_bf16 v[124:127], v[158:161], v[206:209], v[124:127]
	v_mfma_f32_16x16x32_bf16 v[120:123], v[182:185], v[206:209], v[120:123]
	v_mfma_f32_16x16x32_bf16 v[116:119], v[158:161], v[214:217], v[116:119]
	v_mfma_f32_16x16x32_bf16 v[104:107], v[182:185], v[214:217], v[104:107]
	v_mfma_f32_16x16x32_bf16 v[92:95], v[158:161], v[222:225], v[92:95]
	v_mfma_f32_16x16x32_bf16 v[88:91], v[182:185], v[222:225], v[88:91]
	v_mfma_f32_16x16x32_bf16 v[76:79], v[158:161], v[230:233], v[76:79]
	v_mfma_f32_16x16x32_bf16 v[72:75], v[182:185], v[230:233], v[72:75]
	s_setprio 0
	s_setprio 1
	v_mfma_f32_16x16x32_bf16 v[112:115], v[186:189], v[202:205], v[112:115]
	v_mfma_f32_16x16x32_bf16 v[108:111], v[194:197], v[202:205], v[108:111]
	v_mfma_f32_16x16x32_bf16 v[100:103], v[186:189], v[210:213], v[100:103]
	v_mfma_f32_16x16x32_bf16 v[96:99], v[194:197], v[210:213], v[96:99]
	v_mfma_f32_16x16x32_bf16 v[84:87], v[186:189], v[218:221], v[84:87]
	v_mfma_f32_16x16x32_bf16 v[80:83], v[194:197], v[218:221], v[80:83]
	v_mfma_f32_16x16x32_bf16 v[68:71], v[186:189], v[226:229], v[68:71]
	v_mfma_f32_16x16x32_bf16 v[64:67], v[194:197], v[226:229], v[64:67]
	v_mfma_f32_16x16x32_bf16 v[112:115], v[190:193], v[206:209], v[112:115]
	v_mfma_f32_16x16x32_bf16 v[108:111], v[198:201], v[206:209], v[108:111]
	v_mfma_f32_16x16x32_bf16 v[100:103], v[190:193], v[214:217], v[100:103]
	v_mfma_f32_16x16x32_bf16 v[96:99], v[198:201], v[214:217], v[96:99]
	v_mfma_f32_16x16x32_bf16 v[84:87], v[190:193], v[222:225], v[84:87]
	v_mfma_f32_16x16x32_bf16 v[80:83], v[198:201], v[222:225], v[80:83]
	v_mfma_f32_16x16x32_bf16 v[68:71], v[190:193], v[230:233], v[68:71]
	v_mfma_f32_16x16x32_bf16 v[64:67], v[198:201], v[230:233], v[64:67]
	s_setprio 0
	s_barrier
; #define PG8_STAGE(bufoff, gbase, voff) do { _Pragma("unroll") for (int _i = 0; _i < 2; ++_i) \
;         __builtin_amdgcn_global_load_lds((const unsigned*)((const char*)(gbase) + (voff)[_i]), (PG8_LAS unsigned*)(lds + (bufoff) + ldsw + _i * 8192), 16, 0, 0); } while (0)
; #define PG8_LDA(dst, b, h) do { _Pragma("unroll") for (int m = 0; m < 4; ++m) _Pragma("unroll") for (int k = 0; k < 2; ++k) dst[m][k] = *(const PG8_LAS bf16x8*)(lds + PG8_SA(b, h) + aoff + m * 2048 + k * 1024); } while (0)
; #define PG8_MMA(ai, bj, At, Bt) do { __builtin_amdgcn_s_setprio(1); _Pragma("unroll") for (int m = 0; m < 4; ++m) _Pragma("unroll") for (int n = 0; n < 2; ++n) _Pragma("unroll") for (int k = 0; k < 2; ++k) \
;         acc[ai][bj][m][n] = __builtin_amdgcn_mfma_f32_16x16x32_bf16(Bt[n][k], At[m][k], acc[ai][bj][m][n], 0, 0, 0); __builtin_amdgcn_s_setprio(0); } while (0)
; #define PG8_WAIT_V(n) asm volatile("s_waitcnt vmcnt(" #n ")" ::: "memory")
; #define PG8_WAIT_L(n) asm volatile("s_waitcnt lgkmcnt(" #n ")" ::: "memory")
; #define PG8_BAR __builtin_amdgcn_s_barrier()
; #define PG8_SCHED __builtin_amdgcn_sched_barrier(0)
; template <class Epi, class Sched, bool ALIGN_EPI = false, bool SP2 = false>
; __device__ __forceinline__ void gemm_phase(PG8_LAS unsigned char* lds, const Gemm g, const Sched& S, const Epi& E) {
;     ...
;             PG8_LDA(At, 1, 1); PG8_STAGE(PG8_SB(1, 0), b3, voffB); PG8_STAGE(PG8_SB(1, 1), b3 + hstepB, voffB); PG8_STAGE(PG8_SA(1, 0), a3, voffA);
;             PG8_WAIT_V(8); PG8_WAIT_L(0); PG8_BAR; PG8_MMA(1, 0, At, B0); PG8_MMA(1, 1, At, B1); PG8_BAR; PG8_SCHED;
;     ...
;         if constexpr (ALIGN_EPI) { if (wr == 0) PG8_BAR; }
	s_add_i32 s40, s61, s44
	v_lshl_add_u64 v[162:163], v[162:163], 0, s[14:15]
	s_mov_b32 m0, s40
	ds_read_b128 v[202:205], v170 offset:49152
	ds_read_b128 v[206:209], v170 offset:50176
	ds_read_b128 v[210:213], v170 offset:51200
	ds_read_b128 v[214:217], v170 offset:52224
	ds_read_b128 v[218:221], v170 offset:53248
	ds_read_b128 v[222:225], v170 offset:54272
	ds_read_b128 v[226:229], v170 offset:55296
	ds_read_b128 v[230:233], v170 offset:56320
	global_load_lds_dwordx4 v[162:163], off
	s_add_i32 m0, s40, 0x2000
	s_add_u32 s38, s38, 0x40080
	v_lshl_add_u64 v[162:163], v[174:175], 0, s[14:15]
	s_addc_u32 s39, s39, 0
	s_add_i32 s40, s62, s44
	global_load_lds_dwordx4 v[162:163], off
	v_lshl_add_u64 v[162:163], s[38:39], 0, v[130:131]
	s_mov_b32 m0, s40
	s_nop 0
	global_load_lds_dwordx4 v[162:163], off
	v_lshl_add_u64 v[162:163], s[38:39], 0, v[134:135]
	s_add_i32 m0, s40, 0x2000
	s_nop 0
	global_load_lds_dwordx4 v[162:163], off
	v_lshl_add_u64 v[162:163], v[234:235], 0, s[14:15]
	s_mov_b32 m0, s49
	s_nop 0
	global_load_lds_dwordx4 v[162:163], off
	v_lshl_add_u64 v[162:163], v[236:237], 0, s[14:15]
	s_mov_b32 m0, s50
	s_nop 0
	global_load_lds_dwordx4 v[162:163], off
	s_waitcnt vmcnt(8)
	s_waitcnt lgkmcnt(0)
	s_barrier
	s_setprio 1
	v_mfma_f32_16x16x32_bf16 v[60:63], v[154:157], v[202:205], v[60:63]
	v_mfma_f32_16x16x32_bf16 v[56:59], v[178:181], v[202:205], v[56:59]
	v_mfma_f32_16x16x32_bf16 v[44:47], v[154:157], v[210:213], v[44:47]
	v_mfma_f32_16x16x32_bf16 v[40:43], v[178:181], v[210:213], v[40:43]
	v_mfma_f32_16x16x32_bf16 v[28:31], v[154:157], v[218:221], v[28:31]
	v_mfma_f32_16x16x32_bf16 v[24:27], v[178:181], v[218:221], v[24:27]
	v_mfma_f32_16x16x32_bf16 v[12:15], v[154:157], v[226:229], v[12:15]
	v_mfma_f32_16x16x32_bf16 v[8:11], v[178:181], v[226:229], v[8:11]
	v_mfma_f32_16x16x32_bf16 v[60:63], v[158:161], v[206:209], v[60:63]
	v_mfma_f32_16x16x32_bf16 v[56:59], v[182:185], v[206:209], v[56:59]
	v_mfma_f32_16x16x32_bf16 v[44:47], v[158:161], v[214:217], v[44:47]
	v_mfma_f32_16x16x32_bf16 v[40:43], v[182:185], v[214:217], v[40:43]
	v_mfma_f32_16x16x32_bf16 v[28:31], v[158:161], v[222:225], v[28:31]
	v_mfma_f32_16x16x32_bf16 v[24:27], v[182:185], v[222:225], v[24:27]
	v_mfma_f32_16x16x32_bf16 v[12:15], v[158:161], v[230:233], v[12:15]
	v_mfma_f32_16x16x32_bf16 v[8:11], v[182:185], v[230:233], v[8:11]
	s_setprio 0
	s_setprio 1
	v_mfma_f32_16x16x32_bf16 v[52:55], v[186:189], v[202:205], v[52:55]
	v_mfma_f32_16x16x32_bf16 v[48:51], v[194:197], v[202:205], v[48:51]
	v_mfma_f32_16x16x32_bf16 v[36:39], v[186:189], v[210:213], v[36:39]
	v_mfma_f32_16x16x32_bf16 v[32:35], v[194:197], v[210:213], v[32:35]
	v_mfma_f32_16x16x32_bf16 v[20:23], v[186:189], v[218:221], v[20:23]
	v_mfma_f32_16x16x32_bf16 v[16:19], v[194:197], v[218:221], v[16:19]
	v_mfma_f32_16x16x32_bf16 v[4:7], v[186:189], v[226:229], v[4:7]
	v_mfma_f32_16x16x32_bf16 v[0:3], v[194:197], v[226:229], v[0:3]
	v_mfma_f32_16x16x32_bf16 v[52:55], v[190:193], v[206:209], v[52:55]
	v_mfma_f32_16x16x32_bf16 v[48:51], v[198:201], v[206:209], v[48:51]
	v_mfma_f32_16x16x32_bf16 v[36:39], v[190:193], v[214:217], v[36:39]
	v_mfma_f32_16x16x32_bf16 v[32:35], v[198:201], v[214:217], v[32:35]
	v_mfma_f32_16x16x32_bf16 v[20:23], v[190:193], v[222:225], v[20:23]
	v_mfma_f32_16x16x32_bf16 v[16:19], v[198:201], v[222:225], v[16:19]
	v_mfma_f32_16x16x32_bf16 v[4:7], v[190:193], v[230:233], v[4:7]
	v_mfma_f32_16x16x32_bf16 v[0:3], v[198:201], v[230:233], v[0:3]
	s_setprio 0
	s_barrier
	s_add_i32 s60, s60, 2
	s_add_u32 s36, s36, 0x100
	s_addc_u32 s37, s37, 0
	s_add_u32 s58, s58, 0x100
	s_addc_u32 s59, s59, 0
	s_cmp_gt_u32 s60, 61
	s_cbranch_scc0 .LBB0_737
	s_and_b64 vcc, exec, s[16:17]
	s_cbranch_vccz .LBB0_740
	s_barrier
